# LayerNorm row reductions: DPP row_shr/row_bcast + readlane instead of 6-step ds_bpermute butterflies
# speedup vs baseline: 1.0137x; 1.0038x over previous
; #define GAS __attribute__((address_space(1)))
; __device__ __forceinline__ float bflo(unsigned w) { return __uint_as_float(w << 16); }
; __device__ __forceinline__ float bfhi(unsigned w) { return __uint_as_float(w & 0xffff0000u); }
; __device__ __forceinline__ void ln_phase(const GAS bf16_t* Y, GAS bf16_t* XB, GAS float* OUT, const GAS float* g, const GAS float* bta, bool write_bf) {
;     ...
;     for (int row0 = gw; row0 < T_TOK; row0 += RB * NGW) {
;         u32x2 w[RB][4];
; #pragma unroll
;         for (int r = 0; r < RB; ++r) { const int row = min(row0 + r * NGW, T_TOK - 1); const size_t ro = (size_t)row * DM + 4 * lane;
; #pragma unroll
;             for (int j = 0; j < 4; ++j) w[r][j] = __builtin_nontemporal_load((const GAS u32x2*)(Y + ro + 256 * j)); }
; #pragma unroll
;         for (int r = 0; r < RB; ++r) {
;             const int row = row0 + r * NGW;
;             if (row < T_TOK) {
;                 const size_t ro = (size_t)row * DM + 4 * lane;
;                 f32x4 v[4]; float s = 0.f;
; #pragma unroll
;                 for (int j = 0; j < 4; ++j) { v[j] = (f32x4){bflo(w[r][j].x), bfhi(w[r][j].x), bflo(w[r][j].y), bfhi(w[r][j].y)}; s += (v[j][0] + v[j][1]) + (v[j][2] + v[j][3]); }
; #pragma unroll
;                 for (int o = 1; o < 64; o <<= 1) s += __shfl_xor(s, o);
;                 const float mean = s * (1.f / DM); float s2 = 0.f;
; #pragma unroll
;                 for (int j = 0; j < 4; ++j) { v[j] = v[j] - mean; s2 += (v[j][0] * v[j][0] + v[j][1] * v[j][1]) + (v[j][2] * v[j][2] + v[j][3] * v[j][3]); }
; #pragma unroll
;                 for (int o = 1; o < 64; o <<= 1) s2 += __shfl_xor(s2, o);
;                 const float rstd = 1.f / sqrtf(s2 * (1.f / DM) + LN_EPS);
.LBB0_1282:
	v_ashrrev_i32_e32 v41, 31, v40
	v_lshlrev_b64 v[76:77], 11, v[40:41]
	v_lshl_add_u64 v[38:39], v[34:35], 0, v[76:77]
	global_load_dwordx2 v[42:43], v[38:39], off nt
	global_load_dwordx2 v[44:45], v[38:39], off offset:512 nt
	global_load_dwordx2 v[46:47], v[38:39], off offset:1024 nt
	s_nop 0
	global_load_dwordx2 v[38:39], v[38:39], off offset:1536 nt
	v_readlane_b32 s0, v252, 14
	v_lshl_add_u64 v[76:77], v[36:37], 0, v[76:77]
	s_waitcnt vmcnt(3)
	v_lshlrev_b32_e32 v53, 16, v43
	v_lshlrev_b32_e32 v52, 16, v42
	v_and_b32_e32 v49, 0xffff0000, v43
	v_and_b32_e32 v48, 0xffff0000, v42
	s_waitcnt vmcnt(2)
	v_lshlrev_b32_e32 v59, 16, v45
	v_lshlrev_b32_e32 v58, 16, v44
	v_and_b32_e32 v45, 0xffff0000, v45
	v_and_b32_e32 v44, 0xffff0000, v44
	s_waitcnt vmcnt(1)
	v_lshlrev_b32_e32 v62, 16, v46
	v_and_b32_e32 v63, 0xffff0000, v46
	v_lshlrev_b32_e32 v64, 16, v47
	v_and_b32_e32 v65, 0xffff0000, v47
	v_pk_add_f32 v[42:43], v[52:53], v[48:49]
	v_pk_add_f32 v[46:47], v[58:59], v[44:45]
	s_waitcnt vmcnt(0)
	v_lshlrev_b32_e32 v68, 16, v38
	v_and_b32_e32 v74, 0xffff0000, v38
	v_add_f32_e32 v38, v42, v43
	v_pk_add_f32 v[70:71], v[46:47], v[46:47] op_sel_hi:[0,1]
	v_and_b32_e32 v72, 0xffff0000, v39
	v_add_f32_e32 v69, v62, v63
	v_add_f32_e32 v75, v64, v65
	v_add_f32_e32 v73, 0, v38
	v_lshlrev_b32_e32 v70, 16, v39
	v_pk_add_f32 v[42:43], v[68:69], v[74:75]
	v_pk_add_f32 v[38:39], v[70:71], v[72:73]
	s_nop 0
	v_pk_add_f32 v[38:39], v[42:43], v[38:39]
	v_add_u32_e32 v42, s0, v40
	v_add_f32_e32 v38, v38, v39
	v_mov_b32_e32 v120, v38
	s_nop 1
	v_add_f32_dpp v120, v120, v120 row_shr:1 row_mask:0xf bank_mask:0xf bound_ctrl:0
	s_nop 1
	v_add_f32_dpp v120, v120, v120 row_shr:2 row_mask:0xf bank_mask:0xf bound_ctrl:0
	s_nop 1
	v_add_f32_dpp v120, v120, v120 row_shr:4 row_mask:0xf bank_mask:0xf bound_ctrl:0
	s_nop 1
	v_add_f32_dpp v120, v120, v120 row_shr:8 row_mask:0xf bank_mask:0xf bound_ctrl:0
	s_nop 1
	v_add_f32_dpp v120, v120, v120 row_bcast:15 row_mask:0xa bank_mask:0xf
	s_nop 1
	v_add_f32_dpp v120, v120, v120 row_bcast:31 row_mask:0xc bank_mask:0xf
	s_nop 1
	v_readlane_b32 s98, v120, 63
	s_nop 1
	v_readlane_b32 s0, v252, 15
	v_min_i32_e32 v50, 0xffff, v42
	v_ashrrev_i32_e32 v51, 31, v50
	v_lshlrev_b64 v[50:51], 11, v[50:51]
	s_waitcnt lgkmcnt(0)
	v_add_u32_e32 v38, s5, v40
	v_add_u32_e32 v40, s0, v40
	v_min_i32_e32 v46, 0xffff, v38
	v_min_i32_e32 v54, 0xffff, v40
	v_ashrrev_i32_e32 v47, 31, v46
	v_ashrrev_i32_e32 v55, 31, v54
	v_lshlrev_b64 v[46:47], 11, v[46:47]
	v_lshl_add_u64 v[46:47], v[34:35], 0, v[46:47]
	s_mov_b32 s0, 0xf800000
	v_mov_b32_e32 v39, s98
	v_fmac_f32_e32 v48, 0xba800000, v39
	v_fmac_f32_e32 v49, 0xba800000, v39
	v_fmac_f32_e32 v53, 0xba800000, v39
	v_fmac_f32_e32 v44, 0xba800000, v39
	v_fmac_f32_e32 v45, 0xba800000, v39
	v_fmac_f32_e32 v59, 0xba800000, v39
	v_fmac_f32_e32 v52, 0xba800000, v39
	v_fmac_f32_e32 v58, 0xba800000, v39
	v_fmac_f32_e32 v62, 0xba800000, v39
	v_fmac_f32_e32 v64, 0xba800000, v39
	v_mov_b32_e32 v78, v53
	v_mov_b32_e32 v79, v49
	v_mov_b32_e32 v53, v48
	v_mov_b32_e32 v80, v59
	v_mov_b32_e32 v81, v45
	v_mov_b32_e32 v59, v44
	v_fmac_f32_e32 v63, 0xba800000, v39
	v_fmac_f32_e32 v65, 0xba800000, v39
	v_mul_f32_e32 v44, v62, v62
	v_mul_f32_e32 v48, v64, v64
	v_pk_mul_f32 v[56:57], v[78:79], v[78:79]
	v_pk_mul_f32 v[60:61], v[52:53], v[52:53]
	v_pk_mul_f32 v[66:67], v[80:81], v[80:81]
	v_pk_mul_f32 v[82:83], v[58:59], v[58:59]
	v_fmac_f32_e32 v74, 0xba800000, v39
	v_fmac_f32_e32 v68, 0xba800000, v39
	v_pk_fma_f32 v[44:45], v[62:63], v[62:63], v[44:45] op_sel_hi:[1,1,0]
	v_pk_fma_f32 v[48:49], v[64:65], v[64:65], v[48:49] op_sel_hi:[1,1,0]
	v_pk_mov_b32 v[84:85], v[60:61], v[56:57] op_sel:[1,0]
	v_mov_b32_e32 v61, v57
	v_pk_mov_b32 v[56:57], v[82:83], v[66:67] op_sel:[1,0]
	v_mov_b32_e32 v83, v67
	v_mul_f32_e32 v44, v68, v68
	v_mul_f32_e32 v48, v74, v74
	v_pk_add_f32 v[60:61], v[84:85], v[60:61]
	v_pk_add_f32 v[56:57], v[56:57], v[82:83]
	v_fmac_f32_e32 v72, 0xba800000, v39
	v_fmac_f32_e32 v70, 0xba800000, v39
	v_pk_add_f32 v[44:45], v[44:45], v[48:49]
	v_pk_add_f32 v[48:49], v[60:61], v[60:61] op_sel_hi:[0,1]
	v_pk_add_f32 v[56:57], v[56:57], v[56:57] op_sel_hi:[0,1]
	v_mul_f32_e32 v48, v70, v70
	v_mul_f32_e32 v56, v72, v72
	v_pk_add_f32 v[48:49], v[48:49], v[56:57]
	global_load_dwordx2 v[88:89], v[46:47], off nt
	global_load_dwordx2 v[86:87], v[46:47], off offset:512 nt
	global_load_dwordx2 v[84:85], v[46:47], off offset:1024 nt
	global_load_dwordx2 v[82:83], v[46:47], off offset:1536 nt
	v_pk_add_f32 v[44:45], v[44:45], v[48:49]
	v_lshl_add_u64 v[48:49], v[34:35], 0, v[50:51]
	v_add_f32_e32 v39, v44, v45
	v_lshlrev_b64 v[44:45], 11, v[54:55]
	v_lshl_add_u64 v[44:45], v[34:35], 0, v[44:45]
	global_load_dwordx2 v[66:67], v[48:49], off nt
	global_load_dwordx2 v[60:61], v[48:49], off offset:512 nt
	global_load_dwordx2 v[56:57], v[48:49], off offset:1024 nt
	global_load_dwordx2 v[54:55], v[48:49], off offset:1536 nt
	global_load_dwordx2 v[50:51], v[44:45], off nt
	s_nop 0
	global_load_dwordx2 v[48:49], v[44:45], off offset:512 nt
	global_load_dwordx2 v[46:47], v[44:45], off offset:1024 nt
	s_nop 0
	global_load_dwordx2 v[44:45], v[44:45], off offset:1536 nt
	v_mov_b32_e32 v120, v39
	s_nop 1
	v_add_f32_dpp v120, v120, v120 row_shr:1 row_mask:0xf bank_mask:0xf bound_ctrl:0
	s_nop 1
	v_add_f32_dpp v120, v120, v120 row_shr:2 row_mask:0xf bank_mask:0xf bound_ctrl:0
	s_nop 1
	v_add_f32_dpp v120, v120, v120 row_shr:4 row_mask:0xf bank_mask:0xf bound_ctrl:0
	s_nop 1
	v_add_f32_dpp v120, v120, v120 row_shr:8 row_mask:0xf bank_mask:0xf bound_ctrl:0
	s_nop 1
	v_add_f32_dpp v120, v120, v120 row_bcast:15 row_mask:0xa bank_mask:0xf
	s_nop 1
	v_add_f32_dpp v120, v120, v120 row_bcast:31 row_mask:0xc bank_mask:0xf
	s_nop 1
	v_readlane_b32 s98, v120, 63
	s_nop 1
	v_mov_b32_e32 v69, v74
	s_waitcnt lgkmcnt(0)
; #define GAS __attribute__((address_space(1)))
; __device__ __forceinline__ unsigned cvtpk(float lo, float hi) { f32x2_t v = {lo, hi}; bf16x2_t b = __builtin_convertvector(v, bf16x2_t); return __builtin_bit_cast(unsigned, b); }
; __device__ __forceinline__ float bflo(unsigned w) { return __uint_as_float(w << 16); }
; __device__ __forceinline__ float bfhi(unsigned w) { return __uint_as_float(w & 0xffff0000u); }
; __device__ __forceinline__ void ln_phase(const GAS bf16_t* Y, GAS bf16_t* XB, GAS float* OUT, const GAS float* g, const GAS float* bta, bool write_bf) {
;     ...
;         for (int r = 0; r < RB; ++r) {
;             const int row = row0 + r * NGW;
;             if (row < T_TOK) {
;                 const size_t ro = (size_t)row * DM + 4 * lane;
;                 f32x4 v[4]; float s = 0.f;
; #pragma unroll
;                 for (int j = 0; j < 4; ++j) { v[j] = (f32x4){bflo(w[r][j].x), bfhi(w[r][j].x), bflo(w[r][j].y), bfhi(w[r][j].y)}; s += (v[j][0] + v[j][1]) + (v[j][2] + v[j][3]); }
; #pragma unroll
;                 for (int o = 1; o < 64; o <<= 1) s += __shfl_xor(s, o);
;                 const float mean = s * (1.f / DM); float s2 = 0.f;
; #pragma unroll
;                 for (int j = 0; j < 4; ++j) { v[j] = v[j] - mean; s2 += (v[j][0] * v[j][0] + v[j][1] * v[j][1]) + (v[j][2] * v[j][2] + v[j][3] * v[j][3]); }
; #pragma unroll
;                 for (int o = 1; o < 64; o <<= 1) s2 += __shfl_xor(s2, o);
;                 const float rstd = 1.f / sqrtf(s2 * (1.f / DM) + LN_EPS);
; #pragma unroll
;                 for (int j = 0; j < 4; ++j) { const f32x4 y = v[j] * rstd * gv[j] + bv[j];
;                     if (write_bf) { u32x2 o2; o2.x = cvtpk(y[0], y[1]); o2.y = cvtpk(y[2], y[3]); *(GAS u32x2*)(XB + ro + 256 * j) = o2; }
	v_mov_b32_e32 v39, s98
	v_fmamk_f32 v39, v39, 0x3a800000, v227
	v_mul_f32_e32 v41, 0x4f800000, v39
	v_cmp_gt_f32_e32 vcc, s0, v39
	s_nop 1
	v_cndmask_b32_e32 v39, v39, v41, vcc
	v_sqrt_f32_e32 v41, v39
	s_nop 0
	v_add_u32_e32 v43, -1, v41
	v_add_u32_e32 v71, 1, v41
	v_fma_f32 v73, -v43, v41, v39
	v_fma_f32 v74, -v71, v41, v39
	v_cmp_ge_f32_e64 s[0:1], 0, v73
	s_nop 1
	v_cndmask_b32_e64 v41, v41, v43, s[0:1]
	v_cmp_lt_f32_e64 s[0:1], 0, v74
	s_nop 1
	v_cndmask_b32_e64 v41, v41, v71, s[0:1]
	v_mul_f32_e32 v43, 0x37800000, v41
	v_cndmask_b32_e32 v41, v41, v43, vcc
	v_cmp_class_f32_e32 vcc, v39, v222
	v_mov_b32_e32 v71, v72
	s_nop 0
	v_cndmask_b32_e32 v39, v41, v39, vcc
	v_div_scale_f32 v41, s[0:1], v39, v39, 1.0
	v_rcp_f32_e32 v43, v41
	v_div_scale_f32 v72, vcc, 1.0, v39, 1.0
	s_mov_b32 s0, 0x10000
	v_fma_f32 v73, -v41, v43, 1.0
	v_fmac_f32_e32 v43, v73, v43
	v_mul_f32_e32 v73, v72, v43
	v_fma_f32 v74, -v41, v73, v72
	v_fmac_f32_e32 v73, v74, v43
	v_fma_f32 v41, -v41, v73, v72
	v_div_fmas_f32 v41, v41, v43, v73
	v_div_fixup_f32 v72, v41, v39, 1.0
	v_pk_mul_f32 v[52:53], v[52:53], v[72:73] op_sel_hi:[1,0]
	v_pk_mul_f32 v[74:75], v[78:79], v[72:73] op_sel_hi:[1,0]
	v_pk_mul_f32 v[58:59], v[58:59], v[72:73] op_sel_hi:[1,0]
	v_pk_mul_f32 v[78:79], v[80:81], v[72:73] op_sel_hi:[1,0]
	v_pk_mul_f32 v[62:63], v[62:63], v[72:73] op_sel_hi:[1,0]
	v_pk_mul_f32 v[64:65], v[64:65], v[72:73] op_sel_hi:[1,0]
	v_pk_mul_f32 v[68:69], v[68:69], v[72:73] op_sel_hi:[1,0]
	v_pk_mul_f32 v[70:71], v[70:71], v[72:73] op_sel_hi:[1,0]
	v_pk_fma_f32 v[72:73], v[4:5], v[74:75], v[12:13]
	v_pk_fma_f32 v[52:53], v[2:3], v[52:53], v[10:11]
	v_pk_fma_f32 v[74:75], v[8:9], v[78:79], v[16:17]
	v_pk_fma_f32 v[58:59], v[6:7], v[58:59], v[14:15]
	v_pk_fma_f32 v[64:65], v[20:21], v[64:65], v[28:29]
	v_pk_fma_f32 v[62:63], v[18:19], v[62:63], v[26:27]
	v_pk_fma_f32 v[70:71], v[24:25], v[70:71], v[32:33]
	v_pk_fma_f32 v[68:69], v[22:23], v[68:69], v[30:31]
	v_cvt_pk_bf16_f32 v52, v52, v53
	v_cvt_pk_bf16_f32 v53, v72, v73
	v_cmp_gt_i32_e32 vcc, s0, v38
	v_cvt_pk_bf16_f32 v58, v58, v59
	v_cvt_pk_bf16_f32 v59, v74, v75
	v_cvt_pk_bf16_f32 v62, v62, v63
	v_cvt_pk_bf16_f32 v63, v64, v65
	v_cvt_pk_bf16_f32 v64, v68, v69
	v_cvt_pk_bf16_f32 v65, v70, v71
	global_store_dwordx2 v[76:77], v[52:53], off
	global_store_dwordx2 v[76:77], v[58:59], off offset:512
	global_store_dwordx2 v[76:77], v[62:63], off offset:1024
	global_store_dwordx2 v[76:77], v[64:65], off offset:1536
	s_and_saveexec_b64 s[10:11], vcc
	s_cbranch_execz .LBB0_1284
	s_waitcnt vmcnt(15)
	v_lshlrev_b32_e32 v53, 16, v89
	v_lshlrev_b32_e32 v52, 16, v88
	v_and_b32_e32 v59, 0xffff0000, v89
	v_and_b32_e32 v58, 0xffff0000, v88
	s_waitcnt vmcnt(14)
	v_lshlrev_b32_e32 v65, 16, v87
	v_lshlrev_b32_e32 v64, 16, v86
	v_and_b32_e32 v69, 0xffff0000, v87
	v_and_b32_e32 v68, 0xffff0000, v86
	v_pk_add_f32 v[62:63], v[52:53], v[58:59]
	v_pk_add_f32 v[70:71], v[64:65], v[68:69]
	v_add_f32_e32 v39, v62, v63
	s_waitcnt vmcnt(13)
	v_lshlrev_b32_e32 v72, 16, v84
	v_and_b32_e32 v73, 0xffff0000, v84
	v_lshlrev_b32_e32 v74, 16, v85
	v_and_b32_e32 v75, 0xffff0000, v85
	s_waitcnt vmcnt(12)
	v_and_b32_e32 v81, 0xffff0000, v82
	v_pk_add_f32 v[70:71], v[70:71], v[70:71] op_sel:[0,1] op_sel_hi:[1,0]
	v_add_f32_e32 v62, 0, v39
	v_add_f32_e32 v76, v72, v73
	v_add_f32_e32 v78, v74, v75
	v_lshlrev_b32_e32 v63, 16, v82
	v_lshlrev_b32_e32 v77, 16, v83
	v_and_b32_e32 v79, 0xffff0000, v83
	v_mov_b32_e32 v71, v81
	v_pk_add_f32 v[70:71], v[62:63], v[70:71]
	v_pk_add_f32 v[82:83], v[76:77], v[78:79]
	s_mov_b32 s0, 0xf800000
	v_pk_add_f32 v[70:71], v[70:71], v[82:83]
	s_nop 0
	v_add_f32_e32 v39, v70, v71
	v_mov_b32_e32 v120, v39
	s_nop 1
	v_add_f32_dpp v120, v120, v120 row_shr:1 row_mask:0xf bank_mask:0xf bound_ctrl:0
	s_nop 1
	v_add_f32_dpp v120, v120, v120 row_shr:2 row_mask:0xf bank_mask:0xf bound_ctrl:0
	s_nop 1
	v_add_f32_dpp v120, v120, v120 row_shr:4 row_mask:0xf bank_mask:0xf bound_ctrl:0
	s_nop 1
	v_add_f32_dpp v120, v120, v120 row_shr:8 row_mask:0xf bank_mask:0xf bound_ctrl:0
	s_nop 1
	v_add_f32_dpp v120, v120, v120 row_bcast:15 row_mask:0xa bank_mask:0xf
	s_nop 1
	v_add_f32_dpp v120, v120, v120 row_bcast:31 row_mask:0xc bank_mask:0xf
	s_nop 1
	v_readlane_b32 s98, v120, 63
	s_nop 1
	s_waitcnt lgkmcnt(0)
	v_mov_b32_e32 v39, s98
	v_fmac_f32_e32 v58, 0xba800000, v39
	v_fmac_f32_e32 v59, 0xba800000, v39
	v_fmac_f32_e32 v53, 0xba800000, v39
	v_fmac_f32_e32 v52, 0xba800000, v39
	v_mov_b32_e32 v70, v53
	v_mov_b32_e32 v71, v59
	v_mov_b32_e32 v53, v58
	v_pk_mul_f32 v[82:83], v[70:71], v[70:71]
	v_pk_mul_f32 v[58:59], v[52:53], v[52:53]
	v_fmac_f32_e32 v68, 0xba800000, v39
	v_pk_mov_b32 v[84:85], v[58:59], v[82:83] op_sel:[1,0]
	v_mov_b32_e32 v59, v83
	v_fmac_f32_e32 v69, 0xba800000, v39
	v_fmac_f32_e32 v65, 0xba800000, v39
	v_pk_add_f32 v[58:59], v[84:85], v[58:59]
	v_fmac_f32_e32 v64, 0xba800000, v39
	v_mov_b32_e32 v82, v65
	v_mov_b32_e32 v83, v69
	v_mov_b32_e32 v65, v68
	v_pk_add_f32 v[58:59], v[58:59], v[58:59] op_sel_hi:[0,1]
	v_pk_mul_f32 v[84:85], v[82:83], v[82:83]
	v_pk_mul_f32 v[68:69], v[64:65], v[64:65]
	v_fmac_f32_e32 v72, 0xba800000, v39
	v_pk_mov_b32 v[86:87], v[68:69], v[84:85] op_sel:[1,0]
	v_mov_b32_e32 v69, v85
	v_fmac_f32_e32 v73, 0xba800000, v39
	v_fmac_f32_e32 v74, 0xba800000, v39
	v_mul_f32_e32 v58, v72, v72
	v_pk_add_f32 v[68:69], v[86:87], v[68:69]
	v_fmac_f32_e32 v75, 0xba800000, v39
	v_pk_fma_f32 v[84:85], v[72:73], v[72:73], v[58:59] op_sel_hi:[1,1,0]
	v_mul_f32_e32 v58, v74, v74
	v_pk_add_f32 v[68:69], v[68:69], v[68:69] op_sel_hi:[0,1]
	v_pk_fma_f32 v[86:87], v[74:75], v[74:75], v[58:59] op_sel_hi:[1,1,0]
	v_fmac_f32_e32 v79, 0xba800000, v39
	v_fmac_f32_e32 v77, 0xba800000, v39
	v_fmac_f32_e32 v81, 0xba800000, v39
	v_fmac_f32_e32 v63, 0xba800000, v39
	v_mul_f32_e32 v84, v63, v63
	v_mul_f32_e32 v86, v81, v81
	v_mul_f32_e32 v58, v77, v77
	v_mul_f32_e32 v68, v79, v79
	v_pk_add_f32 v[84:85], v[84:85], v[86:87]
	v_pk_add_f32 v[58:59], v[58:59], v[68:69]
	v_mov_b32_e32 v80, v63
	v_pk_add_f32 v[58:59], v[84:85], v[58:59]
	v_mov_b32_e32 v78, v77
	v_add_f32_e32 v39, v58, v59
	v_mov_b32_e32 v120, v39
	s_nop 1
	v_add_f32_dpp v120, v120, v120 row_shr:1 row_mask:0xf bank_mask:0xf bound_ctrl:0
	s_nop 1
	v_add_f32_dpp v120, v120, v120 row_shr:2 row_mask:0xf bank_mask:0xf bound_ctrl:0
	s_nop 1
	v_add_f32_dpp v120, v120, v120 row_shr:4 row_mask:0xf bank_mask:0xf bound_ctrl:0
	s_nop 1
	v_add_f32_dpp v120, v120, v120 row_shr:8 row_mask:0xf bank_mask:0xf bound_ctrl:0
	s_nop 1
	v_add_f32_dpp v120, v120, v120 row_bcast:15 row_mask:0xa bank_mask:0xf
	s_nop 1
	v_add_f32_dpp v120, v120, v120 row_bcast:31 row_mask:0xc bank_mask:0xf
	s_nop 1
	v_readlane_b32 s98, v120, 63
	s_nop 1
	s_waitcnt lgkmcnt(0)
; #define GAS __attribute__((address_space(1)))
; __device__ __forceinline__ unsigned cvtpk(float lo, float hi) { f32x2_t v = {lo, hi}; bf16x2_t b = __builtin_convertvector(v, bf16x2_t); return __builtin_bit_cast(unsigned, b); }
; __device__ __forceinline__ float bflo(unsigned w) { return __uint_as_float(w << 16); }
; __device__ __forceinline__ float bfhi(unsigned w) { return __uint_as_float(w & 0xffff0000u); }
; __device__ __forceinline__ void ln_phase(const GAS bf16_t* Y, GAS bf16_t* XB, GAS float* OUT, const GAS float* g, const GAS float* bta, bool write_bf) {
;     ...
;         for (int r = 0; r < RB; ++r) {
;             const int row = row0 + r * NGW;
;             if (row < T_TOK) {
;                 const size_t ro = (size_t)row * DM + 4 * lane;
;                 f32x4 v[4]; float s = 0.f;
; #pragma unroll
;                 for (int j = 0; j < 4; ++j) { v[j] = (f32x4){bflo(w[r][j].x), bfhi(w[r][j].x), bflo(w[r][j].y), bfhi(w[r][j].y)}; s += (v[j][0] + v[j][1]) + (v[j][2] + v[j][3]); }
; #pragma unroll
;                 for (int o = 1; o < 64; o <<= 1) s += __shfl_xor(s, o);
;                 const float mean = s * (1.f / DM); float s2 = 0.f;
; #pragma unroll
;                 for (int j = 0; j < 4; ++j) { v[j] = v[j] - mean; s2 += (v[j][0] * v[j][0] + v[j][1] * v[j][1]) + (v[j][2] * v[j][2] + v[j][3] * v[j][3]); }
; #pragma unroll
;                 for (int o = 1; o < 64; o <<= 1) s2 += __shfl_xor(s2, o);
;                 const float rstd = 1.f / sqrtf(s2 * (1.f / DM) + LN_EPS);
; #pragma unroll
;                 for (int j = 0; j < 4; ++j) { const f32x4 y = v[j] * rstd * gv[j] + bv[j];
;                     if (write_bf) { u32x2 o2; o2.x = cvtpk(y[0], y[1]); o2.y = cvtpk(y[2], y[3]); *(GAS u32x2*)(XB + ro + 256 * j) = o2; }
	v_mov_b32_e32 v39, s98
	v_fmamk_f32 v39, v39, 0x3a800000, v227
	v_mul_f32_e32 v41, 0x4f800000, v39
	v_cmp_gt_f32_e32 vcc, s0, v39
	s_nop 1
	v_cndmask_b32_e32 v39, v39, v41, vcc
	v_sqrt_f32_e32 v41, v39
	s_nop 0
	v_add_u32_e32 v43, -1, v41
	v_fma_f32 v58, -v43, v41, v39
	v_cmp_ge_f32_e64 s[0:1], 0, v58
	v_add_u32_e32 v58, 1, v41
	s_nop 0
	v_cndmask_b32_e64 v43, v41, v43, s[0:1]
	v_fma_f32 v41, -v58, v41, v39
	v_cmp_lt_f32_e64 s[0:1], 0, v41
	s_nop 1
	v_cndmask_b32_e64 v41, v43, v58, s[0:1]
	v_mul_f32_e32 v43, 0x37800000, v41
	v_cndmask_b32_e32 v41, v41, v43, vcc
	v_cmp_class_f32_e32 vcc, v39, v222
	s_nop 1
	v_cndmask_b32_e32 v41, v41, v39, vcc
	v_div_scale_f32 v43, s[0:1], v41, v41, 1.0
	v_rcp_f32_e32 v58, v43
	v_ashrrev_i32_e32 v39, 31, v38
	v_fma_f32 v59, -v43, v58, 1.0
	v_fmac_f32_e32 v58, v59, v58
	v_div_scale_f32 v59, vcc, 1.0, v41, 1.0
	v_mul_f32_e32 v62, v59, v58
	v_fma_f32 v68, -v43, v62, v59
	v_fmac_f32_e32 v62, v68, v58
	v_fma_f32 v43, -v43, v62, v59
	v_div_fmas_f32 v43, v43, v58, v62
	v_div_fixup_f32 v58, v43, v41, 1.0
	v_pk_mul_f32 v[52:53], v[52:53], v[58:59] op_sel_hi:[1,0]
	v_pk_mul_f32 v[70:71], v[70:71], v[58:59] op_sel_hi:[1,0]
	v_lshlrev_b64 v[68:69], 11, v[38:39]
	v_pk_fma_f32 v[70:71], v[4:5], v[70:71], v[12:13]
	v_pk_fma_f32 v[52:53], v[2:3], v[52:53], v[10:11]
	v_lshl_add_u64 v[68:69], v[36:37], 0, v[68:69]
	v_cvt_pk_bf16_f32 v52, v52, v53
	v_cvt_pk_bf16_f32 v53, v70, v71
	global_store_dwordx2 v[68:69], v[52:53], off
	v_pk_mul_f32 v[52:53], v[64:65], v[58:59] op_sel_hi:[1,0]
	v_pk_mul_f32 v[64:65], v[82:83], v[58:59] op_sel_hi:[1,0]
	v_pk_fma_f32 v[52:53], v[6:7], v[52:53], v[14:15]
	v_pk_fma_f32 v[64:65], v[8:9], v[64:65], v[16:17]
	v_cvt_pk_bf16_f32 v52, v52, v53
	v_cvt_pk_bf16_f32 v53, v64, v65
	global_store_dwordx2 v[68:69], v[52:53], off offset:512
	v_pk_mul_f32 v[52:53], v[72:73], v[58:59] op_sel_hi:[1,0]
	v_pk_mul_f32 v[64:65], v[74:75], v[58:59] op_sel_hi:[1,0]
	v_pk_fma_f32 v[52:53], v[18:19], v[52:53], v[26:27]
	v_pk_fma_f32 v[64:65], v[20:21], v[64:65], v[28:29]
	v_cvt_pk_bf16_f32 v52, v52, v53
	v_cvt_pk_bf16_f32 v53, v64, v65
	global_store_dwordx2 v[68:69], v[52:53], off offset:1024
	v_pk_mul_f32 v[52:53], v[80:81], v[58:59] op_sel_hi:[1,0]
	v_pk_mul_f32 v[58:59], v[78:79], v[58:59] op_sel_hi:[1,0]
	v_pk_fma_f32 v[52:53], v[22:23], v[52:53], v[30:31]
	v_pk_fma_f32 v[58:59], v[24:25], v[58:59], v[32:33]
	v_cvt_pk_bf16_f32 v52, v52, v53
	v_cvt_pk_bf16_f32 v53, v58, v59
	global_store_dwordx2 v[68:69], v[52:53], off offset:1536
.LBB0_1284:
	s_or_b64 exec, exec, s[10:11]
	s_mov_b32 s0, 0x10000
	v_cmp_gt_i32_e32 vcc, s0, v42
	s_and_saveexec_b64 s[10:11], vcc
	s_cbranch_execz .LBB0_1286
	s_waitcnt vmcnt(11)
	v_lshlrev_b32_e32 v53, 16, v67
	v_lshlrev_b32_e32 v52, 16, v66
	v_and_b32_e32 v59, 0xffff0000, v67
	v_and_b32_e32 v58, 0xffff0000, v66
	s_waitcnt vmcnt(10)
	v_lshlrev_b32_e32 v65, 16, v61
	v_lshlrev_b32_e32 v64, 16, v60
	v_and_b32_e32 v61, 0xffff0000, v61
	v_and_b32_e32 v60, 0xffff0000, v60
	v_pk_add_f32 v[62:63], v[52:53], v[58:59]
	v_pk_add_f32 v[66:67], v[64:65], v[60:61]
	v_add_f32_e32 v39, v62, v63
	s_waitcnt vmcnt(9)
	v_lshlrev_b32_e32 v68, 16, v56
	v_and_b32_e32 v69, 0xffff0000, v56
	v_lshlrev_b32_e32 v56, 16, v57
	v_and_b32_e32 v57, 0xffff0000, v57
	s_waitcnt vmcnt(8)
	v_lshlrev_b32_e32 v63, 16, v54
	v_and_b32_e32 v75, 0xffff0000, v54
	v_lshlrev_b32_e32 v71, 16, v55
	v_and_b32_e32 v73, 0xffff0000, v55
	v_pk_add_f32 v[54:55], v[66:67], v[66:67] op_sel:[0,1] op_sel_hi:[1,0]
	v_add_f32_e32 v62, 0, v39
	v_add_f32_e32 v70, v68, v69
	v_add_f32_e32 v72, v56, v57
	v_mov_b32_e32 v55, v75
	v_pk_add_f32 v[54:55], v[62:63], v[54:55]
	v_pk_add_f32 v[66:67], v[70:71], v[72:73]
	s_mov_b32 s0, 0xf800000
	v_pk_add_f32 v[54:55], v[54:55], v[66:67]
	s_nop 0
	v_add_f32_e32 v39, v54, v55
	v_mov_b32_e32 v120, v39
	s_nop 1
	v_add_f32_dpp v120, v120, v120 row_shr:1 row_mask:0xf bank_mask:0xf bound_ctrl:0
	s_nop 1
	v_add_f32_dpp v120, v120, v120 row_shr:2 row_mask:0xf bank_mask:0xf bound_ctrl:0
	s_nop 1
	v_add_f32_dpp v120, v120, v120 row_shr:4 row_mask:0xf bank_mask:0xf bound_ctrl:0
	s_nop 1
	v_add_f32_dpp v120, v120, v120 row_shr:8 row_mask:0xf bank_mask:0xf bound_ctrl:0
	s_nop 1
	v_add_f32_dpp v120, v120, v120 row_bcast:15 row_mask:0xa bank_mask:0xf
	s_nop 1
	v_add_f32_dpp v120, v120, v120 row_bcast:31 row_mask:0xc bank_mask:0xf
	s_nop 1
	v_readlane_b32 s98, v120, 63
	s_nop 1
	s_waitcnt lgkmcnt(0)
	v_mov_b32_e32 v39, s98
	v_fmac_f32_e32 v58, 0xba800000, v39
	v_fmac_f32_e32 v59, 0xba800000, v39
	v_fmac_f32_e32 v53, 0xba800000, v39
	v_fmac_f32_e32 v52, 0xba800000, v39
	v_mov_b32_e32 v54, v53
	v_mov_b32_e32 v55, v59
	v_mov_b32_e32 v53, v58
	v_pk_mul_f32 v[66:67], v[54:55], v[54:55]
	v_pk_mul_f32 v[58:59], v[52:53], v[52:53]
	v_fmac_f32_e32 v60, 0xba800000, v39
	v_pk_mov_b32 v[76:77], v[58:59], v[66:67] op_sel:[1,0]
	v_mov_b32_e32 v59, v67
	v_fmac_f32_e32 v61, 0xba800000, v39
	v_fmac_f32_e32 v65, 0xba800000, v39
	v_pk_add_f32 v[58:59], v[76:77], v[58:59]
	v_fmac_f32_e32 v64, 0xba800000, v39
	v_mov_b32_e32 v66, v65
	v_mov_b32_e32 v67, v61
	v_mov_b32_e32 v65, v60
	v_pk_add_f32 v[58:59], v[58:59], v[58:59] op_sel_hi:[0,1]
	v_pk_mul_f32 v[76:77], v[66:67], v[66:67]
	v_pk_mul_f32 v[60:61], v[64:65], v[64:65]
	v_fmac_f32_e32 v68, 0xba800000, v39
	v_pk_mov_b32 v[78:79], v[60:61], v[76:77] op_sel:[1,0]
	v_mov_b32_e32 v61, v77
	v_fmac_f32_e32 v69, 0xba800000, v39
	v_fmac_f32_e32 v56, 0xba800000, v39
	v_mul_f32_e32 v58, v68, v68
	v_pk_add_f32 v[60:61], v[78:79], v[60:61]
	v_fmac_f32_e32 v57, 0xba800000, v39
	v_pk_fma_f32 v[76:77], v[68:69], v[68:69], v[58:59] op_sel_hi:[1,1,0]
	v_mul_f32_e32 v58, v56, v56
	v_pk_add_f32 v[60:61], v[60:61], v[60:61] op_sel_hi:[0,1]
	v_pk_fma_f32 v[78:79], v[56:57], v[56:57], v[58:59] op_sel_hi:[1,1,0]
	v_fmac_f32_e32 v73, 0xba800000, v39
	v_fmac_f32_e32 v71, 0xba800000, v39
	v_fmac_f32_e32 v75, 0xba800000, v39
	v_fmac_f32_e32 v63, 0xba800000, v39
	v_mul_f32_e32 v76, v63, v63
	v_mul_f32_e32 v78, v75, v75
	v_mul_f32_e32 v58, v71, v71
	v_mul_f32_e32 v60, v73, v73
	v_pk_add_f32 v[76:77], v[76:77], v[78:79]
	v_pk_add_f32 v[58:59], v[58:59], v[60:61]
	v_mov_b32_e32 v74, v63
	v_pk_add_f32 v[58:59], v[76:77], v[58:59]
	v_mov_b32_e32 v72, v71
	v_add_f32_e32 v39, v58, v59
	v_mov_b32_e32 v120, v39
	s_nop 1
	v_add_f32_dpp v120, v120, v120 row_shr:1 row_mask:0xf bank_mask:0xf bound_ctrl:0
	s_nop 1
	v_add_f32_dpp v120, v120, v120 row_shr:2 row_mask:0xf bank_mask:0xf bound_ctrl:0
	s_nop 1
	v_add_f32_dpp v120, v120, v120 row_shr:4 row_mask:0xf bank_mask:0xf bound_ctrl:0
	s_nop 1
	v_add_f32_dpp v120, v120, v120 row_shr:8 row_mask:0xf bank_mask:0xf bound_ctrl:0
	s_nop 1
	v_add_f32_dpp v120, v120, v120 row_bcast:15 row_mask:0xa bank_mask:0xf
	s_nop 1
	v_add_f32_dpp v120, v120, v120 row_bcast:31 row_mask:0xc bank_mask:0xf
	s_nop 1
	v_readlane_b32 s98, v120, 63
	s_nop 1
	s_waitcnt lgkmcnt(0)
; #define GAS __attribute__((address_space(1)))
; __device__ __forceinline__ unsigned cvtpk(float lo, float hi) { f32x2_t v = {lo, hi}; bf16x2_t b = __builtin_convertvector(v, bf16x2_t); return __builtin_bit_cast(unsigned, b); }
; __device__ __forceinline__ void ln_phase(const GAS bf16_t* Y, GAS bf16_t* XB, GAS float* OUT, const GAS float* g, const GAS float* bta, bool write_bf) {
;     ...
;                 const float mean = s * (1.f / DM); float s2 = 0.f;
; #pragma unroll
;                 for (int j = 0; j < 4; ++j) { v[j] = v[j] - mean; s2 += (v[j][0] * v[j][0] + v[j][1] * v[j][1]) + (v[j][2] * v[j][2] + v[j][3] * v[j][3]); }
; #pragma unroll
;                 for (int o = 1; o < 64; o <<= 1) s2 += __shfl_xor(s2, o);
;                 const float rstd = 1.f / sqrtf(s2 * (1.f / DM) + LN_EPS);
; #pragma unroll
;                 for (int j = 0; j < 4; ++j) { const f32x4 y = v[j] * rstd * gv[j] + bv[j];
;                     if (write_bf) { u32x2 o2; o2.x = cvtpk(y[0], y[1]); o2.y = cvtpk(y[2], y[3]); *(GAS u32x2*)(XB + ro + 256 * j) = o2; }
	v_mov_b32_e32 v39, s98
	v_fmamk_f32 v39, v39, 0x3a800000, v227
	v_mul_f32_e32 v41, 0x4f800000, v39
	v_cmp_gt_f32_e32 vcc, s0, v39
	s_nop 1
	v_cndmask_b32_e32 v39, v39, v41, vcc
	v_sqrt_f32_e32 v41, v39
	s_nop 0
	v_add_u32_e32 v43, -1, v41
	v_fma_f32 v58, -v43, v41, v39
	v_cmp_ge_f32_e64 s[0:1], 0, v58
	v_add_u32_e32 v58, 1, v41
	s_nop 0
	v_cndmask_b32_e64 v43, v41, v43, s[0:1]
	v_fma_f32 v41, -v58, v41, v39
	v_cmp_lt_f32_e64 s[0:1], 0, v41
	s_nop 1
	v_cndmask_b32_e64 v41, v43, v58, s[0:1]
	v_mul_f32_e32 v43, 0x37800000, v41
	v_cndmask_b32_e32 v41, v41, v43, vcc
	v_cmp_class_f32_e32 vcc, v39, v222
	v_ashrrev_i32_e32 v43, 31, v42
	v_lshlrev_b64 v[42:43], 11, v[42:43]
	v_cndmask_b32_e32 v39, v41, v39, vcc
	v_div_scale_f32 v41, s[0:1], v39, v39, 1.0
	v_rcp_f32_e32 v58, v41
	v_lshl_add_u64 v[42:43], v[36:37], 0, v[42:43]
	v_fma_f32 v59, -v41, v58, 1.0
	v_fmac_f32_e32 v58, v59, v58
	v_div_scale_f32 v59, vcc, 1.0, v39, 1.0
	v_mul_f32_e32 v60, v59, v58
	v_fma_f32 v61, -v41, v60, v59
	v_fmac_f32_e32 v60, v61, v58
	v_fma_f32 v41, -v41, v60, v59
	v_div_fmas_f32 v41, v41, v58, v60
	v_div_fixup_f32 v58, v41, v39, 1.0
	v_pk_mul_f32 v[52:53], v[52:53], v[58:59] op_sel_hi:[1,0]
	v_pk_mul_f32 v[54:55], v[54:55], v[58:59] op_sel_hi:[1,0]
	v_pk_fma_f32 v[52:53], v[2:3], v[52:53], v[10:11]
	v_pk_fma_f32 v[54:55], v[4:5], v[54:55], v[12:13]
	v_cvt_pk_bf16_f32 v52, v52, v53
	v_cvt_pk_bf16_f32 v53, v54, v55
	global_store_dwordx2 v[42:43], v[52:53], off
	v_pk_mul_f32 v[52:53], v[64:65], v[58:59] op_sel_hi:[1,0]
	v_pk_mul_f32 v[54:55], v[66:67], v[58:59] op_sel_hi:[1,0]
	v_pk_fma_f32 v[52:53], v[6:7], v[52:53], v[14:15]
	v_pk_fma_f32 v[54:55], v[8:9], v[54:55], v[16:17]
	v_cvt_pk_bf16_f32 v52, v52, v53
	v_cvt_pk_bf16_f32 v53, v54, v55
	global_store_dwordx2 v[42:43], v[52:53], off offset:512
	v_pk_mul_f32 v[52:53], v[68:69], v[58:59] op_sel_hi:[1,0]
	v_pk_mul_f32 v[54:55], v[56:57], v[58:59] op_sel_hi:[1,0]
	v_pk_fma_f32 v[52:53], v[18:19], v[52:53], v[26:27]
	v_pk_fma_f32 v[54:55], v[20:21], v[54:55], v[28:29]
	v_cvt_pk_bf16_f32 v52, v52, v53
	v_cvt_pk_bf16_f32 v53, v54, v55
	global_store_dwordx2 v[42:43], v[52:53], off offset:1024
	v_pk_mul_f32 v[52:53], v[74:75], v[58:59] op_sel_hi:[1,0]
	v_pk_mul_f32 v[54:55], v[72:73], v[58:59] op_sel_hi:[1,0]
	v_pk_fma_f32 v[52:53], v[22:23], v[52:53], v[30:31]
	v_pk_fma_f32 v[54:55], v[24:25], v[54:55], v[32:33]
	v_cvt_pk_bf16_f32 v52, v52, v53
	v_cvt_pk_bf16_f32 v53, v54, v55
	global_store_dwordx2 v[42:43], v[52:53], off offset:1536
; #define GAS __attribute__((address_space(1)))
; __device__ __forceinline__ unsigned cvtpk(float lo, float hi) { f32x2_t v = {lo, hi}; bf16x2_t b = __builtin_convertvector(v, bf16x2_t); return __builtin_bit_cast(unsigned, b); }
; __device__ __forceinline__ float bflo(unsigned w) { return __uint_as_float(w << 16); }
; __device__ __forceinline__ float bfhi(unsigned w) { return __uint_as_float(w & 0xffff0000u); }
; __device__ __forceinline__ void ln_phase(const GAS bf16_t* Y, GAS bf16_t* XB, GAS float* OUT, const GAS float* g, const GAS float* bta, bool write_bf) {
;     ...
;         for (int r = 0; r < RB; ++r) {
;             const int row = row0 + r * NGW;
;             if (row < T_TOK) {
;                 const size_t ro = (size_t)row * DM + 4 * lane;
;                 f32x4 v[4]; float s = 0.f;
; #pragma unroll
;                 for (int j = 0; j < 4; ++j) { v[j] = (f32x4){bflo(w[r][j].x), bfhi(w[r][j].x), bflo(w[r][j].y), bfhi(w[r][j].y)}; s += (v[j][0] + v[j][1]) + (v[j][2] + v[j][3]); }
; #pragma unroll
;                 for (int o = 1; o < 64; o <<= 1) s += __shfl_xor(s, o);
;                 const float mean = s * (1.f / DM); float s2 = 0.f;
; #pragma unroll
;                 for (int j = 0; j < 4; ++j) { v[j] = v[j] - mean; s2 += (v[j][0] * v[j][0] + v[j][1] * v[j][1]) + (v[j][2] * v[j][2] + v[j][3] * v[j][3]); }
; #pragma unroll
;                 for (int o = 1; o < 64; o <<= 1) s2 += __shfl_xor(s2, o);
;                 const float rstd = 1.f / sqrtf(s2 * (1.f / DM) + LN_EPS);
; #pragma unroll
;                 for (int j = 0; j < 4; ++j) { const f32x4 y = v[j] * rstd * gv[j] + bv[j];
;                     if (write_bf) { u32x2 o2; o2.x = cvtpk(y[0], y[1]); o2.y = cvtpk(y[2], y[3]); *(GAS u32x2*)(XB + ro + 256 * j) = o2; }
.LBB0_1286:
	s_or_b64 exec, exec, s[10:11]
	s_mov_b32 s0, 0x10000
	v_cmp_gt_i32_e32 vcc, s0, v40
	s_and_saveexec_b64 s[10:11], vcc
	s_cbranch_execz .LBB0_1281
	s_waitcnt vmcnt(7)
	v_lshlrev_b32_e32 v43, 16, v51
	v_lshlrev_b32_e32 v42, 16, v50
	v_and_b32_e32 v51, 0xffff0000, v51
	v_and_b32_e32 v50, 0xffff0000, v50
	s_waitcnt vmcnt(6)
	v_lshlrev_b32_e32 v55, 16, v49
	v_lshlrev_b32_e32 v54, 16, v48
	v_and_b32_e32 v49, 0xffff0000, v49
	v_and_b32_e32 v48, 0xffff0000, v48
	v_pk_add_f32 v[52:53], v[42:43], v[50:51]
	v_pk_add_f32 v[56:57], v[54:55], v[48:49]
	v_add_f32_e32 v39, v52, v53
	s_waitcnt vmcnt(5)
	v_lshlrev_b32_e32 v58, 16, v46
	v_and_b32_e32 v59, 0xffff0000, v46
	v_lshlrev_b32_e32 v46, 16, v47
	v_and_b32_e32 v47, 0xffff0000, v47
	s_waitcnt vmcnt(4)
	v_lshlrev_b32_e32 v53, 16, v44
	v_and_b32_e32 v65, 0xffff0000, v44
	v_lshlrev_b32_e32 v61, 16, v45
	v_and_b32_e32 v63, 0xffff0000, v45
	v_pk_add_f32 v[44:45], v[56:57], v[56:57] op_sel:[0,1] op_sel_hi:[1,0]
	v_add_f32_e32 v52, 0, v39
	v_add_f32_e32 v60, v58, v59
	v_add_f32_e32 v62, v46, v47
	v_mov_b32_e32 v45, v65
	v_pk_add_f32 v[44:45], v[52:53], v[44:45]
	v_pk_add_f32 v[56:57], v[60:61], v[62:63]
	s_mov_b32 s0, 0xf800000
	v_pk_add_f32 v[44:45], v[44:45], v[56:57]
	s_nop 0
	v_add_f32_e32 v39, v44, v45
	v_mov_b32_e32 v120, v39
	s_nop 1
	v_add_f32_dpp v120, v120, v120 row_shr:1 row_mask:0xf bank_mask:0xf bound_ctrl:0
	s_nop 1
	v_add_f32_dpp v120, v120, v120 row_shr:2 row_mask:0xf bank_mask:0xf bound_ctrl:0
	s_nop 1
	v_add_f32_dpp v120, v120, v120 row_shr:4 row_mask:0xf bank_mask:0xf bound_ctrl:0
	s_nop 1
	v_add_f32_dpp v120, v120, v120 row_shr:8 row_mask:0xf bank_mask:0xf bound_ctrl:0
	s_nop 1
	v_add_f32_dpp v120, v120, v120 row_bcast:15 row_mask:0xa bank_mask:0xf
	s_nop 1
	v_add_f32_dpp v120, v120, v120 row_bcast:31 row_mask:0xc bank_mask:0xf
	s_nop 1
	v_readlane_b32 s98, v120, 63
	s_nop 1
	s_waitcnt lgkmcnt(0)
	v_mov_b32_e32 v39, s98
	v_fmac_f32_e32 v50, 0xba800000, v39
	v_fmac_f32_e32 v51, 0xba800000, v39
	v_fmac_f32_e32 v43, 0xba800000, v39
	v_fmac_f32_e32 v42, 0xba800000, v39
	v_mov_b32_e32 v44, v43
	v_mov_b32_e32 v45, v51
	v_mov_b32_e32 v43, v50
	v_pk_mul_f32 v[56:57], v[44:45], v[44:45]
	v_pk_mul_f32 v[50:51], v[42:43], v[42:43]
	v_fmac_f32_e32 v48, 0xba800000, v39
	v_fmac_f32_e32 v49, 0xba800000, v39
	v_fmac_f32_e32 v55, 0xba800000, v39
	v_pk_mov_b32 v[66:67], v[50:51], v[56:57] op_sel:[1,0]
	v_mov_b32_e32 v51, v57
	v_fmac_f32_e32 v54, 0xba800000, v39
	v_mov_b32_e32 v56, v55
	v_mov_b32_e32 v57, v49
	v_mov_b32_e32 v55, v48
	v_pk_add_f32 v[50:51], v[66:67], v[50:51]
	v_pk_mul_f32 v[66:67], v[56:57], v[56:57]
	v_pk_mul_f32 v[48:49], v[54:55], v[54:55]
	v_fmac_f32_e32 v58, 0xba800000, v39
	v_pk_mov_b32 v[68:69], v[48:49], v[66:67] op_sel:[1,0]
	v_mov_b32_e32 v49, v67
	v_pk_add_f32 v[48:49], v[68:69], v[48:49]
	v_fmac_f32_e32 v59, 0xba800000, v39
	v_pk_add_f32 v[48:49], v[48:49], v[48:49] op_sel_hi:[0,1]
	v_fmac_f32_e32 v46, 0xba800000, v39
	v_mul_f32_e32 v48, v58, v58
	v_fmac_f32_e32 v47, 0xba800000, v39
	v_pk_fma_f32 v[66:67], v[58:59], v[58:59], v[48:49] op_sel_hi:[1,1,0]
	v_mul_f32_e32 v48, v46, v46
	v_pk_add_f32 v[50:51], v[50:51], v[50:51] op_sel_hi:[0,1]
	v_pk_fma_f32 v[68:69], v[46:47], v[46:47], v[48:49] op_sel_hi:[1,1,0]
	v_fmac_f32_e32 v63, 0xba800000, v39
	v_fmac_f32_e32 v61, 0xba800000, v39
	v_fmac_f32_e32 v65, 0xba800000, v39
	v_fmac_f32_e32 v53, 0xba800000, v39
	v_mul_f32_e32 v66, v53, v53
	v_mul_f32_e32 v68, v65, v65
	v_mul_f32_e32 v50, v61, v61
	v_mul_f32_e32 v48, v63, v63
	v_pk_add_f32 v[66:67], v[66:67], v[68:69]
	v_pk_add_f32 v[48:49], v[50:51], v[48:49]
	v_mov_b32_e32 v64, v53
	v_pk_add_f32 v[48:49], v[66:67], v[48:49]
	v_mov_b32_e32 v62, v61
	v_add_f32_e32 v39, v48, v49
	v_mov_b32_e32 v120, v39
	s_nop 1
	v_add_f32_dpp v120, v120, v120 row_shr:1 row_mask:0xf bank_mask:0xf bound_ctrl:0
	s_nop 1
	v_add_f32_dpp v120, v120, v120 row_shr:2 row_mask:0xf bank_mask:0xf bound_ctrl:0
	s_nop 1
	v_add_f32_dpp v120, v120, v120 row_shr:4 row_mask:0xf bank_mask:0xf bound_ctrl:0
	s_nop 1
	v_add_f32_dpp v120, v120, v120 row_shr:8 row_mask:0xf bank_mask:0xf bound_ctrl:0
	s_nop 1
	v_add_f32_dpp v120, v120, v120 row_bcast:15 row_mask:0xa bank_mask:0xf
	s_nop 1
	v_add_f32_dpp v120, v120, v120 row_bcast:31 row_mask:0xc bank_mask:0xf
	s_nop 1
	v_readlane_b32 s98, v120, 63
	s_nop 1
	s_waitcnt lgkmcnt(0)
	v_mov_b32_e32 v39, s98
	v_fmamk_f32 v39, v39, 0x3a800000, v227
	v_mul_f32_e32 v41, 0x4f800000, v39
	v_cmp_gt_f32_e32 vcc, s0, v39
	s_nop 1
	v_cndmask_b32_e32 v39, v39, v41, vcc
	v_sqrt_f32_e32 v41, v39
	s_nop 0
	v_add_u32_e32 v48, -1, v41
	v_fma_f32 v49, -v48, v41, v39
	v_cmp_ge_f32_e64 s[0:1], 0, v49
	v_add_u32_e32 v49, 1, v41
	s_nop 0
	v_cndmask_b32_e64 v48, v41, v48, s[0:1]
	v_fma_f32 v41, -v49, v41, v39
	v_cmp_lt_f32_e64 s[0:1], 0, v41
	s_nop 1
	v_cndmask_b32_e64 v41, v48, v49, s[0:1]
	v_mul_f32_e32 v48, 0x37800000, v41
	v_cndmask_b32_e32 v41, v41, v48, vcc
	v_cmp_class_f32_e32 vcc, v39, v222
	s_nop 1
	v_cndmask_b32_e32 v39, v41, v39, vcc
	v_div_scale_f32 v48, s[0:1], v39, v39, 1.0
	v_rcp_f32_e32 v49, v48
	v_ashrrev_i32_e32 v41, 31, v40
	v_lshlrev_b64 v[40:41], 11, v[40:41]
	v_lshl_add_u64 v[40:41], v[36:37], 0, v[40:41]
	v_fma_f32 v50, -v48, v49, 1.0
	v_fmac_f32_e32 v49, v50, v49
	v_div_scale_f32 v50, vcc, 1.0, v39, 1.0
	v_mul_f32_e32 v51, v50, v49
	v_fma_f32 v52, -v48, v51, v50
	v_fmac_f32_e32 v51, v52, v49
	v_fma_f32 v48, -v48, v51, v50
	v_div_fmas_f32 v48, v48, v49, v51
	v_div_fixup_f32 v48, v48, v39, 1.0
	v_pk_mul_f32 v[42:43], v[42:43], v[48:49] op_sel_hi:[1,0]
	v_pk_mul_f32 v[44:45], v[44:45], v[48:49] op_sel_hi:[1,0]
	v_pk_fma_f32 v[42:43], v[2:3], v[42:43], v[10:11]
	v_pk_fma_f32 v[44:45], v[4:5], v[44:45], v[12:13]
	v_cvt_pk_bf16_f32 v42, v42, v43
	v_cvt_pk_bf16_f32 v43, v44, v45
	global_store_dwordx2 v[40:41], v[42:43], off
	v_pk_mul_f32 v[42:43], v[54:55], v[48:49] op_sel_hi:[1,0]
	v_pk_mul_f32 v[44:45], v[56:57], v[48:49] op_sel_hi:[1,0]
	v_pk_fma_f32 v[42:43], v[6:7], v[42:43], v[14:15]
	v_pk_fma_f32 v[44:45], v[8:9], v[44:45], v[16:17]
	v_cvt_pk_bf16_f32 v42, v42, v43
	v_cvt_pk_bf16_f32 v43, v44, v45
	global_store_dwordx2 v[40:41], v[42:43], off offset:512
	v_pk_mul_f32 v[42:43], v[58:59], v[48:49] op_sel_hi:[1,0]
	v_pk_mul_f32 v[44:45], v[46:47], v[48:49] op_sel_hi:[1,0]
	v_pk_fma_f32 v[42:43], v[18:19], v[42:43], v[26:27]
	v_pk_fma_f32 v[44:45], v[20:21], v[44:45], v[28:29]
	v_cvt_pk_bf16_f32 v42, v42, v43
	v_cvt_pk_bf16_f32 v43, v44, v45
	global_store_dwordx2 v[40:41], v[42:43], off offset:1024
	v_pk_mul_f32 v[42:43], v[64:65], v[48:49] op_sel_hi:[1,0]
	v_pk_mul_f32 v[44:45], v[62:63], v[48:49] op_sel_hi:[1,0]
	v_pk_fma_f32 v[42:43], v[22:23], v[42:43], v[30:31]
	v_pk_fma_f32 v[44:45], v[24:25], v[44:45], v[32:33]
	v_cvt_pk_bf16_f32 v42, v42, v43
	v_cvt_pk_bf16_f32 v43, v44, v45
	global_store_dwordx2 v[40:41], v[42:43], off offset:1536
	s_branch .LBB0_1281

; #define GAS __attribute__((address_space(1)))
; __device__ __forceinline__ float bflo(unsigned w) { return __uint_as_float(w << 16); }
; __device__ __forceinline__ float bfhi(unsigned w) { return __uint_as_float(w & 0xffff0000u); }
; __device__ __forceinline__ void ln_phase(const GAS bf16_t* Y, GAS bf16_t* XB, GAS float* OUT, const GAS float* g, const GAS float* bta, bool write_bf) {
;     ...
;     for (int row0 = gw; row0 < T_TOK; row0 += RB * NGW) {
;         u32x2 w[RB][4];
; #pragma unroll
;         for (int r = 0; r < RB; ++r) { const int row = min(row0 + r * NGW, T_TOK - 1); const size_t ro = (size_t)row * DM + 4 * lane;
; #pragma unroll
;             for (int j = 0; j < 4; ++j) w[r][j] = __builtin_nontemporal_load((const GAS u32x2*)(Y + ro + 256 * j)); }
; #pragma unroll
;         for (int r = 0; r < RB; ++r) {
;             const int row = row0 + r * NGW;
;             if (row < T_TOK) {
;                 const size_t ro = (size_t)row * DM + 4 * lane;
;                 f32x4 v[4]; float s = 0.f;
; #pragma unroll
;                 for (int j = 0; j < 4; ++j) { v[j] = (f32x4){bflo(w[r][j].x), bfhi(w[r][j].x), bflo(w[r][j].y), bfhi(w[r][j].y)}; s += (v[j][0] + v[j][1]) + (v[j][2] + v[j][3]); }
; #pragma unroll
;                 for (int o = 1; o < 64; o <<= 1) s += __shfl_xor(s, o);
;                 const float mean = s * (1.f / DM); float s2 = 0.f;
.LBB0_1582:
	v_add_u32_e32 v42, s15, v34
	v_min_i32_e32 v36, 0xffff, v42
	v_ashrrev_i32_e32 v37, 31, v36
	v_lshlrev_b64 v[36:37], 11, v[36:37]
	v_readlane_b32 s0, v252, 14
	v_lshl_add_u64 v[36:37], v[40:41], 0, v[36:37]
	global_load_dwordx2 v[70:71], v[36:37], off nt
	global_load_dwordx2 v[68:69], v[36:37], off offset:512 nt
	global_load_dwordx2 v[66:67], v[36:37], off offset:1024 nt
	global_load_dwordx2 v[64:65], v[36:37], off offset:1536 nt
	v_add_u32_e32 v54, s0, v34
	v_min_i32_e32 v36, 0xffff, v54
	v_ashrrev_i32_e32 v37, 31, v36
	v_lshlrev_b64 v[36:37], 11, v[36:37]
	v_readlane_b32 s0, v252, 15
	v_lshl_add_u64 v[36:37], v[40:41], 0, v[36:37]
	global_load_dwordx2 v[62:63], v[36:37], off nt
	global_load_dwordx2 v[60:61], v[36:37], off offset:512 nt
	global_load_dwordx2 v[58:59], v[36:37], off offset:1024 nt
	global_load_dwordx2 v[56:57], v[36:37], off offset:1536 nt
	v_add_u32_e32 v44, s0, v34
	v_min_i32_e32 v36, 0xffff, v44
	v_ashrrev_i32_e32 v37, 31, v36
	v_lshlrev_b64 v[36:37], 11, v[36:37]
	v_lshl_add_u64 v[36:37], v[40:41], 0, v[36:37]
	v_ashrrev_i32_e32 v35, 31, v34
	global_load_dwordx2 v[52:53], v[36:37], off nt
	global_load_dwordx2 v[50:51], v[36:37], off offset:512 nt
	global_load_dwordx2 v[48:49], v[36:37], off offset:1024 nt
	global_load_dwordx2 v[46:47], v[36:37], off offset:1536 nt
	v_lshlrev_b64 v[36:37], 11, v[34:35]
	v_lshl_add_u64 v[36:37], v[40:41], 0, v[36:37]
	global_load_dwordx2 v[90:91], v[36:37], off offset:1536 nt
	global_load_dwordx2 v[76:77], v[36:37], off offset:1024 nt
	global_load_dwordx2 v[74:75], v[36:37], off offset:512 nt
	s_nop 0
	global_load_dwordx2 v[36:37], v[36:37], off nt
	v_lshlrev_b64 v[80:81], 10, v[34:35]
	s_mov_b32 s0, 0xf800000
	v_or_b32_e32 v80, v80, v38
	s_waitcnt vmcnt(3)
	v_and_b32_e32 v78, 0xffff0000, v90
	s_waitcnt vmcnt(2)
	v_lshlrev_b32_e32 v82, 16, v76
	s_waitcnt vmcnt(1)
	v_lshlrev_b32_e32 v87, 16, v75
	s_waitcnt vmcnt(0)
	v_lshlrev_b32_e32 v35, 16, v37
	v_lshlrev_b32_e32 v34, 16, v36
	v_and_b32_e32 v93, 0xffff0000, v37
	v_and_b32_e32 v92, 0xffff0000, v36
	v_pk_add_f32 v[36:37], v[34:35], v[92:93]
	v_lshlrev_b32_e32 v86, 16, v74
	v_add_f32_e32 v36, v36, v37
	v_and_b32_e32 v89, 0xffff0000, v75
	v_and_b32_e32 v88, 0xffff0000, v74
	v_add_f32_e32 v73, 0, v36
	v_pk_add_f32 v[36:37], v[86:87], v[88:89]
	v_and_b32_e32 v83, 0xffff0000, v76
	v_pk_add_f32 v[74:75], v[36:37], v[36:37] op_sel_hi:[0,1]
	v_lshlrev_b32_e32 v84, 16, v77
	v_and_b32_e32 v85, 0xffff0000, v77
	v_add_f32_e32 v77, v82, v83
	v_add_f32_e32 v79, v84, v85
	v_lshlrev_b32_e32 v76, 16, v90
	v_lshlrev_b32_e32 v74, 16, v91
	v_and_b32_e32 v72, 0xffff0000, v91
	v_pk_add_f32 v[36:37], v[76:77], v[78:79]
	v_pk_add_f32 v[90:91], v[74:75], v[72:73]
	s_nop 0
	v_pk_add_f32 v[36:37], v[36:37], v[90:91]
	s_nop 0
	v_add_f32_e32 v36, v36, v37
	v_mov_b32_e32 v120, v36
	s_nop 1
	v_add_f32_dpp v120, v120, v120 row_shr:1 row_mask:0xf bank_mask:0xf bound_ctrl:0
	s_nop 1
	v_add_f32_dpp v120, v120, v120 row_shr:2 row_mask:0xf bank_mask:0xf bound_ctrl:0
	s_nop 1
	v_add_f32_dpp v120, v120, v120 row_shr:4 row_mask:0xf bank_mask:0xf bound_ctrl:0
	s_nop 1
	v_add_f32_dpp v120, v120, v120 row_shr:8 row_mask:0xf bank_mask:0xf bound_ctrl:0
	s_nop 1
	v_add_f32_dpp v120, v120, v120 row_bcast:15 row_mask:0xa bank_mask:0xf
	s_nop 1
	v_add_f32_dpp v120, v120, v120 row_bcast:31 row_mask:0xc bank_mask:0xf
	s_nop 1
	v_readlane_b32 s98, v120, 63
	s_nop 1
	s_waitcnt lgkmcnt(0)
; #define GAS __attribute__((address_space(1)))
; __device__ __forceinline__ unsigned cvtpk(float lo, float hi) { f32x2_t v = {lo, hi}; bf16x2_t b = __builtin_convertvector(v, bf16x2_t); return __builtin_bit_cast(unsigned, b); }
; __device__ __forceinline__ void ln_phase(const GAS bf16_t* Y, GAS bf16_t* XB, GAS float* OUT, const GAS float* g, const GAS float* bta, bool write_bf) {
;     ...
;                 const float mean = s * (1.f / DM); float s2 = 0.f;
; #pragma unroll
;                 for (int j = 0; j < 4; ++j) { v[j] = v[j] - mean; s2 += (v[j][0] * v[j][0] + v[j][1] * v[j][1]) + (v[j][2] * v[j][2] + v[j][3] * v[j][3]); }
; #pragma unroll
;                 for (int o = 1; o < 64; o <<= 1) s2 += __shfl_xor(s2, o);
;                 const float rstd = 1.f / sqrtf(s2 * (1.f / DM) + LN_EPS);
; #pragma unroll
;                 for (int j = 0; j < 4; ++j) { const f32x4 y = v[j] * rstd * gv[j] + bv[j];
;                     if (write_bf) { u32x2 o2; o2.x = cvtpk(y[0], y[1]); o2.y = cvtpk(y[2], y[3]); *(GAS u32x2*)(XB + ro + 256 * j) = o2; }
;                     else __builtin_nontemporal_store(y, (GAS f32x4*)(OUT + ro + 256 * j)); }
	v_mov_b32_e32 v43, s98
	v_fmac_f32_e32 v92, 0xba800000, v43
	v_fmac_f32_e32 v93, 0xba800000, v43
	v_fmac_f32_e32 v35, 0xba800000, v43
	v_fmac_f32_e32 v34, 0xba800000, v43
	v_mov_b32_e32 v36, v35
	v_mov_b32_e32 v37, v93
	v_mov_b32_e32 v35, v92
	v_pk_mul_f32 v[90:91], v[36:37], v[36:37]
	v_pk_mul_f32 v[92:93], v[34:35], v[34:35]
	v_fmac_f32_e32 v89, 0xba800000, v43
	v_pk_mov_b32 v[98:99], v[92:93], v[90:91] op_sel:[1,0]
	v_mov_b32_e32 v93, v91
	v_fmac_f32_e32 v87, 0xba800000, v43
	v_fmac_f32_e32 v88, 0xba800000, v43
	v_fmac_f32_e32 v86, 0xba800000, v43
	v_pk_add_f32 v[90:91], v[98:99], v[92:93]
	v_mov_b32_e32 v92, v87
	v_mov_b32_e32 v93, v89
	v_mov_b32_e32 v98, v86
	v_mov_b32_e32 v99, v88
	v_pk_add_f32 v[90:91], v[90:91], v[90:91] op_sel_hi:[0,1]
	v_pk_mul_f32 v[92:93], v[92:93], v[92:93]
	v_pk_mul_f32 v[98:99], v[98:99], v[98:99]
	v_fmac_f32_e32 v82, 0xba800000, v43
	v_pk_mov_b32 v[100:101], v[98:99], v[92:93] op_sel:[1,0]
	v_mov_b32_e32 v99, v93
	v_fmac_f32_e32 v84, 0xba800000, v43
	v_fmac_f32_e32 v83, 0xba800000, v43
	v_mul_f32_e32 v90, v82, v82
	v_pk_add_f32 v[92:93], v[100:101], v[98:99]
	v_fmac_f32_e32 v85, 0xba800000, v43
	v_pk_fma_f32 v[98:99], v[82:83], v[82:83], v[90:91] op_sel_hi:[1,1,0]
	v_mul_f32_e32 v90, v84, v84
	v_pk_add_f32 v[92:93], v[92:93], v[92:93] op_sel_hi:[0,1]
	v_pk_fma_f32 v[100:101], v[84:85], v[84:85], v[90:91] op_sel_hi:[1,1,0]
	v_fmac_f32_e32 v72, 0xba800000, v43
	v_fmac_f32_e32 v74, 0xba800000, v43
	v_fmac_f32_e32 v78, 0xba800000, v43
	v_fmac_f32_e32 v76, 0xba800000, v43
	v_mul_f32_e32 v98, v76, v76
	v_mul_f32_e32 v100, v78, v78
	v_mul_f32_e32 v90, v74, v74
	v_mul_f32_e32 v92, v72, v72
	v_pk_add_f32 v[98:99], v[98:99], v[100:101]
	v_pk_add_f32 v[90:91], v[90:91], v[92:93]
	s_nop 0
	v_pk_add_f32 v[90:91], v[98:99], v[90:91]
	s_nop 0
	v_add_f32_e32 v43, v90, v91
	v_mov_b32_e32 v120, v43
	s_nop 1
	v_add_f32_dpp v120, v120, v120 row_shr:1 row_mask:0xf bank_mask:0xf bound_ctrl:0
	s_nop 1
	v_add_f32_dpp v120, v120, v120 row_shr:2 row_mask:0xf bank_mask:0xf bound_ctrl:0
	s_nop 1
	v_add_f32_dpp v120, v120, v120 row_shr:4 row_mask:0xf bank_mask:0xf bound_ctrl:0
	s_nop 1
	v_add_f32_dpp v120, v120, v120 row_shr:8 row_mask:0xf bank_mask:0xf bound_ctrl:0
	s_nop 1
	v_add_f32_dpp v120, v120, v120 row_bcast:15 row_mask:0xa bank_mask:0xf
	s_nop 1
	v_add_f32_dpp v120, v120, v120 row_bcast:31 row_mask:0xc bank_mask:0xf
	s_nop 1
	v_readlane_b32 s98, v120, 63
	s_nop 1
	v_lshl_add_u64 v[90:91], v[80:81], 2, s[4:5]
	s_waitcnt lgkmcnt(0)
	v_mov_b32_e32 v43, s98
	v_fmamk_f32 v43, v43, 0x3a800000, v227
	v_cmp_gt_f32_e32 vcc, s0, v43
	v_mul_f32_e32 v45, 0x4f800000, v43
	s_nop 0
	v_cndmask_b32_e32 v43, v43, v45, vcc
	v_sqrt_f32_e32 v45, v43
	s_nop 0
	v_add_u32_e32 v55, -1, v45
	v_fma_f32 v73, -v55, v45, v43
	v_cmp_ge_f32_e64 s[0:1], 0, v73
	v_add_u32_e32 v73, 1, v45
	s_nop 0
	v_cndmask_b32_e64 v55, v45, v55, s[0:1]
	v_fma_f32 v45, -v73, v45, v43
	v_cmp_lt_f32_e64 s[0:1], 0, v45
	s_nop 1
	v_cndmask_b32_e64 v45, v55, v73, s[0:1]
	v_mul_f32_e32 v55, 0x37800000, v45
	v_cndmask_b32_e32 v45, v45, v55, vcc
	v_cmp_class_f32_e32 vcc, v43, v222
	s_nop 1
	v_cndmask_b32_e32 v43, v45, v43, vcc
	v_div_scale_f32 v45, s[0:1], v43, v43, 1.0
	v_rcp_f32_e32 v55, v45
	s_nop 0
	v_fma_f32 v73, -v45, v55, 1.0
	v_fmac_f32_e32 v55, v73, v55
	v_div_scale_f32 v73, vcc, 1.0, v43, 1.0
	v_mul_f32_e32 v75, v73, v55
	v_fma_f32 v77, -v45, v75, v73
	v_fmac_f32_e32 v75, v77, v55
	v_fma_f32 v45, -v45, v75, v73
	v_div_fmas_f32 v45, v45, v55, v75
	v_div_fixup_f32 v92, v45, v43, 1.0
	v_pk_mul_f32 v[34:35], v[34:35], v[92:93] op_sel_hi:[1,0]
	v_pk_mul_f32 v[36:37], v[36:37], v[92:93] op_sel_hi:[1,0]
	v_pk_fma_f32 v[34:35], v[2:3], v[34:35], v[10:11]
	v_pk_fma_f32 v[36:37], v[4:5], v[36:37], v[12:13]
	s_and_b64 vcc, exec, s[10:11]
	s_cbranch_vccz .LBB0_1632
	global_store_dwordx4 v[90:91], v[34:37], off nt
	v_lshl_add_u64 v[80:81], v[80:81], 1, s[8:9]
	s_cbranch_execnz .LBB0_1585

; #define GAS __attribute__((address_space(1)))
; __device__ __forceinline__ unsigned cvtpk(float lo, float hi) { f32x2_t v = {lo, hi}; bf16x2_t b = __builtin_convertvector(v, bf16x2_t); return __builtin_bit_cast(unsigned, b); }
; __device__ __forceinline__ float bflo(unsigned w) { return __uint_as_float(w << 16); }
; __device__ __forceinline__ float bfhi(unsigned w) { return __uint_as_float(w & 0xffff0000u); }
; __device__ __forceinline__ void ln_phase(const GAS bf16_t* Y, GAS bf16_t* XB, GAS float* OUT, const GAS float* g, const GAS float* bta, bool write_bf) {
;     ...
;         for (int r = 0; r < RB; ++r) {
;             const int row = row0 + r * NGW;
;             if (row < T_TOK) {
;                 const size_t ro = (size_t)row * DM + 4 * lane;
;                 f32x4 v[4]; float s = 0.f;
; #pragma unroll
;                 for (int j = 0; j < 4; ++j) { v[j] = (f32x4){bflo(w[r][j].x), bfhi(w[r][j].x), bflo(w[r][j].y), bfhi(w[r][j].y)}; s += (v[j][0] + v[j][1]) + (v[j][2] + v[j][3]); }
; #pragma unroll
;                 for (int o = 1; o < 64; o <<= 1) s += __shfl_xor(s, o);
;                 const float mean = s * (1.f / DM); float s2 = 0.f;
; #pragma unroll
;                 for (int j = 0; j < 4; ++j) { v[j] = v[j] - mean; s2 += (v[j][0] * v[j][0] + v[j][1] * v[j][1]) + (v[j][2] * v[j][2] + v[j][3] * v[j][3]); }
; #pragma unroll
;                 for (int o = 1; o < 64; o <<= 1) s2 += __shfl_xor(s2, o);
;                 const float rstd = 1.f / sqrtf(s2 * (1.f / DM) + LN_EPS);
; #pragma unroll
;                 for (int j = 0; j < 4; ++j) { const f32x4 y = v[j] * rstd * gv[j] + bv[j];
;                     if (write_bf) { u32x2 o2; o2.x = cvtpk(y[0], y[1]); o2.y = cvtpk(y[2], y[3]); *(GAS u32x2*)(XB + ro + 256 * j) = o2; }
;                     else __builtin_nontemporal_store(y, (GAS f32x4*)(OUT + ro + 256 * j)); }
.LBB0_1594:
	s_mov_b32 s2, 0x10000
	v_cmp_gt_i32_e32 vcc, s2, v42
	s_and_saveexec_b64 s[14:15], vcc
	s_cbranch_execz .LBB0_1607
	v_lshlrev_b32_e32 v35, 16, v71
	v_lshlrev_b32_e32 v34, 16, v70
	v_and_b32_e32 v37, 0xffff0000, v71
	v_and_b32_e32 v36, 0xffff0000, v70
	v_lshlrev_b32_e32 v75, 16, v69
	v_lshlrev_b32_e32 v74, 16, v68
	v_and_b32_e32 v79, 0xffff0000, v69
	v_and_b32_e32 v78, 0xffff0000, v68
	v_pk_add_f32 v[70:71], v[34:35], v[36:37]
	v_pk_add_f32 v[80:81], v[74:75], v[78:79]
	v_add_f32_e32 v43, v70, v71
	v_lshlrev_b32_e32 v70, 16, v66
	v_and_b32_e32 v71, 0xffff0000, v66
	v_lshlrev_b32_e32 v72, 16, v67
	v_and_b32_e32 v73, 0xffff0000, v67
	v_lshlrev_b32_e32 v77, 16, v64
	v_and_b32_e32 v69, 0xffff0000, v64
	v_lshlrev_b32_e32 v83, 16, v65
	v_and_b32_e32 v67, 0xffff0000, v65
	v_pk_add_f32 v[64:65], v[80:81], v[80:81] op_sel:[0,1] op_sel_hi:[1,0]
	v_add_f32_e32 v76, 0, v43
	v_add_f32_e32 v82, v70, v71
	v_add_f32_e32 v66, v72, v73
	v_mov_b32_e32 v65, v69
	v_pk_add_f32 v[64:65], v[76:77], v[64:65]
	v_pk_add_f32 v[80:81], v[82:83], v[66:67]
	v_mov_b32_e32 v66, v83
	v_pk_add_f32 v[64:65], v[64:65], v[80:81]
	v_mov_b32_e32 v68, v77
	v_add_f32_e32 v43, v64, v65
	v_mov_b32_e32 v120, v43
	s_nop 1
	v_add_f32_dpp v120, v120, v120 row_shr:1 row_mask:0xf bank_mask:0xf bound_ctrl:0
	s_nop 1
	v_add_f32_dpp v120, v120, v120 row_shr:2 row_mask:0xf bank_mask:0xf bound_ctrl:0
	s_nop 1
	v_add_f32_dpp v120, v120, v120 row_shr:4 row_mask:0xf bank_mask:0xf bound_ctrl:0
	s_nop 1
	v_add_f32_dpp v120, v120, v120 row_shr:8 row_mask:0xf bank_mask:0xf bound_ctrl:0
	s_nop 1
	v_add_f32_dpp v120, v120, v120 row_bcast:15 row_mask:0xa bank_mask:0xf
	s_nop 1
	v_add_f32_dpp v120, v120, v120 row_bcast:31 row_mask:0xc bank_mask:0xf
	s_nop 1
	v_readlane_b32 s98, v120, 63
	s_nop 1
	s_mov_b32 s2, 0xf800000
	s_waitcnt lgkmcnt(0)
	v_mov_b32_e32 v43, s98
	v_fmac_f32_e32 v36, 0xba800000, v43
	v_fmac_f32_e32 v37, 0xba800000, v43
	v_fmac_f32_e32 v35, 0xba800000, v43
	v_fmac_f32_e32 v34, 0xba800000, v43
	v_mov_b32_e32 v84, v35
	v_mov_b32_e32 v85, v37
	v_mov_b32_e32 v35, v36
	v_pk_mul_f32 v[64:65], v[84:85], v[84:85]
	v_pk_mul_f32 v[36:37], v[34:35], v[34:35]
	v_fmac_f32_e32 v74, 0xba800000, v43
	v_pk_mov_b32 v[80:81], v[36:37], v[64:65] op_sel:[1,0]
	v_mov_b32_e32 v37, v65
	v_mov_b32_e32 v65, v79
	v_mov_b32_e32 v64, v75
	v_mov_b32_e32 v75, v78
	v_pk_add_f32 v[36:37], v[80:81], v[36:37]
	v_fmac_f32_e32 v65, 0xba800000, v43
	v_fmac_f32_e32 v64, 0xba800000, v43
	v_fmac_f32_e32 v75, 0xba800000, v43
	v_pk_add_f32 v[36:37], v[36:37], v[36:37] op_sel_hi:[0,1]
	v_pk_mul_f32 v[78:79], v[64:65], v[64:65]
	v_pk_mul_f32 v[80:81], v[74:75], v[74:75]
	v_fmac_f32_e32 v70, 0xba800000, v43
	v_pk_mov_b32 v[86:87], v[80:81], v[78:79] op_sel:[1,0]
	v_mov_b32_e32 v81, v79
	v_fmac_f32_e32 v72, 0xba800000, v43
	v_fmac_f32_e32 v71, 0xba800000, v43
	v_mul_f32_e32 v36, v70, v70
	v_pk_add_f32 v[78:79], v[86:87], v[80:81]
	v_fmac_f32_e32 v73, 0xba800000, v43
	v_pk_fma_f32 v[80:81], v[70:71], v[70:71], v[36:37] op_sel_hi:[1,1,0]
	v_mul_f32_e32 v36, v72, v72
	v_pk_add_f32 v[78:79], v[78:79], v[78:79] op_sel_hi:[0,1]
	v_pk_fma_f32 v[86:87], v[72:73], v[72:73], v[36:37] op_sel_hi:[1,1,0]
	v_fmac_f32_e32 v67, 0xba800000, v43
	v_fmac_f32_e32 v66, 0xba800000, v43
	v_fmac_f32_e32 v69, 0xba800000, v43
	v_fmac_f32_e32 v68, 0xba800000, v43
	v_mul_f32_e32 v80, v68, v68
	v_mul_f32_e32 v86, v69, v69
	v_mul_f32_e32 v36, v66, v66
	v_mul_f32_e32 v78, v67, v67
	v_pk_add_f32 v[76:77], v[80:81], v[86:87]
	v_pk_add_f32 v[36:37], v[36:37], v[78:79]
	s_nop 0
	v_pk_add_f32 v[36:37], v[76:77], v[36:37]
	s_nop 0
	v_add_f32_e32 v36, v36, v37
	v_mov_b32_e32 v120, v36
	s_nop 1
	v_add_f32_dpp v120, v120, v120 row_shr:1 row_mask:0xf bank_mask:0xf bound_ctrl:0
	s_nop 1
	v_add_f32_dpp v120, v120, v120 row_shr:2 row_mask:0xf bank_mask:0xf bound_ctrl:0
	s_nop 1
	v_add_f32_dpp v120, v120, v120 row_shr:4 row_mask:0xf bank_mask:0xf bound_ctrl:0
	s_nop 1
	v_add_f32_dpp v120, v120, v120 row_shr:8 row_mask:0xf bank_mask:0xf bound_ctrl:0
	s_nop 1
	v_add_f32_dpp v120, v120, v120 row_bcast:15 row_mask:0xa bank_mask:0xf
	s_nop 1
	v_add_f32_dpp v120, v120, v120 row_bcast:31 row_mask:0xc bank_mask:0xf
	s_nop 1
	v_readlane_b32 s98, v120, 63
	s_nop 1
	s_waitcnt lgkmcnt(0)
	v_mov_b32_e32 v36, s98
	v_fmamk_f32 v36, v36, 0x3a800000, v227
	v_mul_f32_e32 v37, 0x4f800000, v36
	v_cmp_gt_f32_e32 vcc, s2, v36
	s_nop 1
	v_cndmask_b32_e32 v36, v36, v37, vcc
	v_sqrt_f32_e32 v37, v36
	s_nop 0
	v_add_u32_e32 v43, -1, v37
	v_fma_f32 v45, -v43, v37, v36
	v_cmp_ge_f32_e64 s[2:3], 0, v45
	v_add_u32_e32 v45, 1, v37
	s_nop 0
	v_cndmask_b32_e64 v43, v37, v43, s[2:3]
	v_fma_f32 v37, -v45, v37, v36
	v_cmp_lt_f32_e64 s[2:3], 0, v37
	s_nop 1
	v_cndmask_b32_e64 v37, v43, v45, s[2:3]
	v_mul_f32_e32 v43, 0x37800000, v37
	v_cndmask_b32_e32 v37, v37, v43, vcc
	v_cmp_class_f32_e32 vcc, v36, v222
	v_ashrrev_i32_e32 v43, 31, v42
	v_lshlrev_b64 v[78:79], 10, v[42:43]
	v_cndmask_b32_e32 v36, v37, v36, vcc
	v_div_scale_f32 v37, s[2:3], v36, v36, 1.0
	v_rcp_f32_e32 v45, v37
	v_or_b32_e32 v78, v78, v38
	v_fma_f32 v43, -v37, v45, 1.0
	v_fmac_f32_e32 v45, v43, v45
	v_div_scale_f32 v43, vcc, 1.0, v36, 1.0
	v_mul_f32_e32 v55, v43, v45
	v_fma_f32 v76, -v37, v55, v43
	v_fmac_f32_e32 v55, v76, v45
	v_fma_f32 v37, -v37, v55, v43
	v_div_fmas_f32 v37, v37, v45, v55
	v_div_fixup_f32 v80, v37, v36, 1.0
	v_pk_mul_f32 v[34:35], v[34:35], v[80:81] op_sel_hi:[1,0]
	v_pk_mul_f32 v[36:37], v[84:85], v[80:81] op_sel_hi:[1,0]
	v_lshl_add_u64 v[76:77], v[78:79], 2, s[4:5]
	v_pk_fma_f32 v[36:37], v[4:5], v[36:37], v[12:13]
	s_and_b64 vcc, exec, s[0:1]
	v_pk_fma_f32 v[34:35], v[2:3], v[34:35], v[10:11]
	s_cbranch_vccnz .LBB0_1636
	global_store_dwordx4 v[76:77], v[34:37], off nt
	v_lshl_add_u64 v[78:79], v[78:79], 1, s[8:9]
	s_cbranch_execnz .LBB0_1598

; #define GAS __attribute__((address_space(1)))
; __device__ __forceinline__ unsigned cvtpk(float lo, float hi) { f32x2_t v = {lo, hi}; bf16x2_t b = __builtin_convertvector(v, bf16x2_t); return __builtin_bit_cast(unsigned, b); }
; __device__ __forceinline__ float bflo(unsigned w) { return __uint_as_float(w << 16); }
; __device__ __forceinline__ float bfhi(unsigned w) { return __uint_as_float(w & 0xffff0000u); }
; __device__ __forceinline__ void ln_phase(const GAS bf16_t* Y, GAS bf16_t* XB, GAS float* OUT, const GAS float* g, const GAS float* bta, bool write_bf) {
;     ...
;         for (int r = 0; r < RB; ++r) {
;             const int row = row0 + r * NGW;
;             if (row < T_TOK) {
;                 const size_t ro = (size_t)row * DM + 4 * lane;
;                 f32x4 v[4]; float s = 0.f;
; #pragma unroll
;                 for (int j = 0; j < 4; ++j) { v[j] = (f32x4){bflo(w[r][j].x), bfhi(w[r][j].x), bflo(w[r][j].y), bfhi(w[r][j].y)}; s += (v[j][0] + v[j][1]) + (v[j][2] + v[j][3]); }
; #pragma unroll
;                 for (int o = 1; o < 64; o <<= 1) s += __shfl_xor(s, o);
;                 const float mean = s * (1.f / DM); float s2 = 0.f;
; #pragma unroll
;                 for (int j = 0; j < 4; ++j) { v[j] = v[j] - mean; s2 += (v[j][0] * v[j][0] + v[j][1] * v[j][1]) + (v[j][2] * v[j][2] + v[j][3] * v[j][3]); }
; #pragma unroll
;                 for (int o = 1; o < 64; o <<= 1) s2 += __shfl_xor(s2, o);
;                 const float rstd = 1.f / sqrtf(s2 * (1.f / DM) + LN_EPS);
; #pragma unroll
;                 for (int j = 0; j < 4; ++j) { const f32x4 y = v[j] * rstd * gv[j] + bv[j];
;                     if (write_bf) { u32x2 o2; o2.x = cvtpk(y[0], y[1]); o2.y = cvtpk(y[2], y[3]); *(GAS u32x2*)(XB + ro + 256 * j) = o2; }
;                     else __builtin_nontemporal_store(y, (GAS f32x4*)(OUT + ro + 256 * j)); }
.LBB0_1607:
	s_or_b64 exec, exec, s[14:15]
	s_mov_b32 s2, 0x10000
	v_cmp_gt_i32_e32 vcc, s2, v54
	s_and_saveexec_b64 s[14:15], vcc
	s_cbranch_execz .LBB0_1620
	v_lshlrev_b32_e32 v35, 16, v63
	v_lshlrev_b32_e32 v34, 16, v62
	v_and_b32_e32 v37, 0xffff0000, v63
	v_and_b32_e32 v36, 0xffff0000, v62
	v_lshlrev_b32_e32 v67, 16, v61
	v_lshlrev_b32_e32 v66, 16, v60
	v_and_b32_e32 v71, 0xffff0000, v61
	v_and_b32_e32 v70, 0xffff0000, v60
	v_pk_add_f32 v[62:63], v[34:35], v[36:37]
	v_pk_add_f32 v[72:73], v[66:67], v[70:71]
	v_add_f32_e32 v43, v62, v63
	v_lshlrev_b32_e32 v62, 16, v58
	v_and_b32_e32 v63, 0xffff0000, v58
	v_lshlrev_b32_e32 v64, 16, v59
	v_and_b32_e32 v65, 0xffff0000, v59
	v_lshlrev_b32_e32 v69, 16, v56
	v_and_b32_e32 v61, 0xffff0000, v56
	v_lshlrev_b32_e32 v75, 16, v57
	v_and_b32_e32 v59, 0xffff0000, v57
	v_pk_add_f32 v[56:57], v[72:73], v[72:73] op_sel:[0,1] op_sel_hi:[1,0]
	v_add_f32_e32 v68, 0, v43
	v_add_f32_e32 v74, v62, v63
	v_add_f32_e32 v58, v64, v65
	v_mov_b32_e32 v57, v61
	v_pk_add_f32 v[56:57], v[68:69], v[56:57]
	v_pk_add_f32 v[72:73], v[74:75], v[58:59]
	v_mov_b32_e32 v58, v75
	v_pk_add_f32 v[56:57], v[56:57], v[72:73]
	v_mov_b32_e32 v60, v69
	v_add_f32_e32 v43, v56, v57
	v_mov_b32_e32 v120, v43
	s_nop 1
	v_add_f32_dpp v120, v120, v120 row_shr:1 row_mask:0xf bank_mask:0xf bound_ctrl:0
	s_nop 1
	v_add_f32_dpp v120, v120, v120 row_shr:2 row_mask:0xf bank_mask:0xf bound_ctrl:0
	s_nop 1
	v_add_f32_dpp v120, v120, v120 row_shr:4 row_mask:0xf bank_mask:0xf bound_ctrl:0
	s_nop 1
	v_add_f32_dpp v120, v120, v120 row_shr:8 row_mask:0xf bank_mask:0xf bound_ctrl:0
	s_nop 1
	v_add_f32_dpp v120, v120, v120 row_bcast:15 row_mask:0xa bank_mask:0xf
	s_nop 1
	v_add_f32_dpp v120, v120, v120 row_bcast:31 row_mask:0xc bank_mask:0xf
	s_nop 1
	v_readlane_b32 s98, v120, 63
	s_nop 1
	s_mov_b32 s2, 0xf800000
	v_ashrrev_i32_e32 v55, 31, v54
	s_waitcnt lgkmcnt(0)
	v_mov_b32_e32 v43, s98
	v_fmac_f32_e32 v36, 0xba800000, v43
	v_fmac_f32_e32 v37, 0xba800000, v43
	v_fmac_f32_e32 v35, 0xba800000, v43
	v_fmac_f32_e32 v34, 0xba800000, v43
	v_mov_b32_e32 v72, v35
	v_mov_b32_e32 v73, v37
	v_mov_b32_e32 v35, v36
	v_pk_mul_f32 v[56:57], v[72:73], v[72:73]
	v_pk_mul_f32 v[36:37], v[34:35], v[34:35]
	v_fmac_f32_e32 v66, 0xba800000, v43
	v_pk_mov_b32 v[76:77], v[36:37], v[56:57] op_sel:[1,0]
	v_mov_b32_e32 v37, v57
	v_mov_b32_e32 v57, v71
	v_mov_b32_e32 v56, v67
	v_mov_b32_e32 v67, v70
	v_pk_add_f32 v[36:37], v[76:77], v[36:37]
	v_fmac_f32_e32 v57, 0xba800000, v43
	v_fmac_f32_e32 v56, 0xba800000, v43
	v_fmac_f32_e32 v67, 0xba800000, v43
	v_pk_add_f32 v[36:37], v[36:37], v[36:37] op_sel_hi:[0,1]
	v_pk_mul_f32 v[70:71], v[56:57], v[56:57]
	v_pk_mul_f32 v[76:77], v[66:67], v[66:67]
	v_fmac_f32_e32 v62, 0xba800000, v43
	v_pk_mov_b32 v[78:79], v[76:77], v[70:71] op_sel:[1,0]
	v_mov_b32_e32 v77, v71
	v_fmac_f32_e32 v64, 0xba800000, v43
	v_fmac_f32_e32 v63, 0xba800000, v43
	v_mul_f32_e32 v36, v62, v62
	v_pk_add_f32 v[70:71], v[78:79], v[76:77]
	v_fmac_f32_e32 v65, 0xba800000, v43
	v_pk_fma_f32 v[76:77], v[62:63], v[62:63], v[36:37] op_sel_hi:[1,1,0]
	v_mul_f32_e32 v36, v64, v64
	v_pk_add_f32 v[70:71], v[70:71], v[70:71] op_sel_hi:[0,1]
	v_pk_fma_f32 v[78:79], v[64:65], v[64:65], v[36:37] op_sel_hi:[1,1,0]
	v_fmac_f32_e32 v59, 0xba800000, v43
	v_fmac_f32_e32 v58, 0xba800000, v43
	v_fmac_f32_e32 v61, 0xba800000, v43
	v_fmac_f32_e32 v60, 0xba800000, v43
	v_mul_f32_e32 v76, v60, v60
	v_mul_f32_e32 v78, v61, v61
	v_mul_f32_e32 v36, v58, v58
	v_mul_f32_e32 v70, v59, v59
	v_pk_add_f32 v[68:69], v[76:77], v[78:79]
	v_pk_add_f32 v[36:37], v[36:37], v[70:71]
	s_nop 0
	v_pk_add_f32 v[36:37], v[68:69], v[36:37]
	v_lshlrev_b64 v[68:69], 10, v[54:55]
	v_add_f32_e32 v36, v36, v37
	v_mov_b32_e32 v120, v36
	s_nop 1
	v_add_f32_dpp v120, v120, v120 row_shr:1 row_mask:0xf bank_mask:0xf bound_ctrl:0
	s_nop 1
	v_add_f32_dpp v120, v120, v120 row_shr:2 row_mask:0xf bank_mask:0xf bound_ctrl:0
	s_nop 1
	v_add_f32_dpp v120, v120, v120 row_shr:4 row_mask:0xf bank_mask:0xf bound_ctrl:0
	s_nop 1
	v_add_f32_dpp v120, v120, v120 row_shr:8 row_mask:0xf bank_mask:0xf bound_ctrl:0
	s_nop 1
	v_add_f32_dpp v120, v120, v120 row_bcast:15 row_mask:0xa bank_mask:0xf
	s_nop 1
	v_add_f32_dpp v120, v120, v120 row_bcast:31 row_mask:0xc bank_mask:0xf
	s_nop 1
	v_readlane_b32 s98, v120, 63
	s_nop 1
	v_or_b32_e32 v68, v68, v38
	s_waitcnt lgkmcnt(0)
	v_mov_b32_e32 v36, s98
	v_fmamk_f32 v36, v36, 0x3a800000, v227
	v_mul_f32_e32 v37, 0x4f800000, v36
	v_cmp_gt_f32_e32 vcc, s2, v36
	s_nop 1
	v_cndmask_b32_e32 v36, v36, v37, vcc
	v_sqrt_f32_e32 v37, v36
	s_nop 0
	v_add_u32_e32 v43, -1, v37
	v_fma_f32 v45, -v43, v37, v36
	v_cmp_ge_f32_e64 s[2:3], 0, v45
	v_add_u32_e32 v45, 1, v37
	s_nop 0
	v_cndmask_b32_e64 v43, v37, v43, s[2:3]
	v_fma_f32 v37, -v45, v37, v36
	v_cmp_lt_f32_e64 s[2:3], 0, v37
	s_nop 1
	v_cndmask_b32_e64 v37, v43, v45, s[2:3]
	v_mul_f32_e32 v43, 0x37800000, v37
	v_cndmask_b32_e32 v37, v37, v43, vcc
	v_cmp_class_f32_e32 vcc, v36, v222
	s_nop 1
	v_cndmask_b32_e32 v36, v37, v36, vcc
	v_div_scale_f32 v37, s[2:3], v36, v36, 1.0
	v_rcp_f32_e32 v43, v37
	s_nop 0
	v_fma_f32 v45, -v37, v43, 1.0
	v_fmac_f32_e32 v43, v45, v43
	v_div_scale_f32 v45, vcc, 1.0, v36, 1.0
	v_mul_f32_e32 v54, v45, v43
	v_fma_f32 v55, -v37, v54, v45
	v_fmac_f32_e32 v54, v55, v43
	v_fma_f32 v37, -v37, v54, v45
	v_div_fmas_f32 v37, v37, v43, v54
	v_div_fixup_f32 v70, v37, v36, 1.0
	v_pk_mul_f32 v[34:35], v[34:35], v[70:71] op_sel_hi:[1,0]
	v_pk_mul_f32 v[36:37], v[72:73], v[70:71] op_sel_hi:[1,0]
	v_lshl_add_u64 v[54:55], v[68:69], 2, s[4:5]
	v_pk_fma_f32 v[36:37], v[4:5], v[36:37], v[12:13]
	s_and_b64 vcc, exec, s[0:1]
	v_pk_fma_f32 v[34:35], v[2:3], v[34:35], v[10:11]
	s_cbranch_vccnz .LBB0_1640
	global_store_dwordx4 v[54:55], v[34:37], off nt
	v_lshl_add_u64 v[68:69], v[68:69], 1, s[8:9]
	s_cbranch_execnz .LBB0_1611

; #define GAS __attribute__((address_space(1)))
; __device__ __forceinline__ unsigned cvtpk(float lo, float hi) { f32x2_t v = {lo, hi}; bf16x2_t b = __builtin_convertvector(v, bf16x2_t); return __builtin_bit_cast(unsigned, b); }
; __device__ __forceinline__ float bflo(unsigned w) { return __uint_as_float(w << 16); }
; __device__ __forceinline__ float bfhi(unsigned w) { return __uint_as_float(w & 0xffff0000u); }
; __device__ __forceinline__ void ln_phase(const GAS bf16_t* Y, GAS bf16_t* XB, GAS float* OUT, const GAS float* g, const GAS float* bta, bool write_bf) {
;     ...
;         for (int r = 0; r < RB; ++r) {
;             const int row = row0 + r * NGW;
;             if (row < T_TOK) {
;                 const size_t ro = (size_t)row * DM + 4 * lane;
;                 f32x4 v[4]; float s = 0.f;
; #pragma unroll
;                 for (int j = 0; j < 4; ++j) { v[j] = (f32x4){bflo(w[r][j].x), bfhi(w[r][j].x), bflo(w[r][j].y), bfhi(w[r][j].y)}; s += (v[j][0] + v[j][1]) + (v[j][2] + v[j][3]); }
; #pragma unroll
;                 for (int o = 1; o < 64; o <<= 1) s += __shfl_xor(s, o);
;                 const float mean = s * (1.f / DM); float s2 = 0.f;
; #pragma unroll
;                 for (int j = 0; j < 4; ++j) { v[j] = v[j] - mean; s2 += (v[j][0] * v[j][0] + v[j][1] * v[j][1]) + (v[j][2] * v[j][2] + v[j][3] * v[j][3]); }
; #pragma unroll
;                 for (int o = 1; o < 64; o <<= 1) s2 += __shfl_xor(s2, o);
;                 const float rstd = 1.f / sqrtf(s2 * (1.f / DM) + LN_EPS);
; #pragma unroll
;                 for (int j = 0; j < 4; ++j) { const f32x4 y = v[j] * rstd * gv[j] + bv[j];
;                     if (write_bf) { u32x2 o2; o2.x = cvtpk(y[0], y[1]); o2.y = cvtpk(y[2], y[3]); *(GAS u32x2*)(XB + ro + 256 * j) = o2; }
;                     else __builtin_nontemporal_store(y, (GAS f32x4*)(OUT + ro + 256 * j)); }
.LBB0_1620:
	s_or_b64 exec, exec, s[14:15]
	s_mov_b32 s2, 0x10000
	v_cmp_gt_i32_e32 vcc, s2, v44
	s_and_saveexec_b64 s[14:15], vcc
	s_cbranch_execz .LBB0_1581
	v_lshlrev_b32_e32 v35, 16, v53
	v_lshlrev_b32_e32 v34, 16, v52
	v_and_b32_e32 v37, 0xffff0000, v53
	v_and_b32_e32 v36, 0xffff0000, v52
	v_lshlrev_b32_e32 v57, 16, v51
	v_lshlrev_b32_e32 v56, 16, v50
	v_and_b32_e32 v61, 0xffff0000, v51
	v_and_b32_e32 v60, 0xffff0000, v50
	v_pk_add_f32 v[52:53], v[34:35], v[36:37]
	v_pk_add_f32 v[62:63], v[56:57], v[60:61]
	v_add_f32_e32 v43, v52, v53
	v_lshlrev_b32_e32 v52, 16, v48
	v_and_b32_e32 v53, 0xffff0000, v48
	v_lshlrev_b32_e32 v54, 16, v49
	v_and_b32_e32 v55, 0xffff0000, v49
	v_lshlrev_b32_e32 v59, 16, v46
	v_and_b32_e32 v51, 0xffff0000, v46
	v_lshlrev_b32_e32 v65, 16, v47
	v_and_b32_e32 v49, 0xffff0000, v47
	v_pk_add_f32 v[46:47], v[62:63], v[62:63] op_sel:[0,1] op_sel_hi:[1,0]
	v_add_f32_e32 v58, 0, v43
	v_add_f32_e32 v64, v52, v53
	v_add_f32_e32 v48, v54, v55
	v_mov_b32_e32 v47, v51
	v_pk_add_f32 v[46:47], v[58:59], v[46:47]
	v_pk_add_f32 v[62:63], v[64:65], v[48:49]
	v_mov_b32_e32 v48, v65
	v_pk_add_f32 v[46:47], v[46:47], v[62:63]
	v_mov_b32_e32 v50, v59
	v_add_f32_e32 v43, v46, v47
	v_mov_b32_e32 v120, v43
	s_nop 1
	v_add_f32_dpp v120, v120, v120 row_shr:1 row_mask:0xf bank_mask:0xf bound_ctrl:0
	s_nop 1
	v_add_f32_dpp v120, v120, v120 row_shr:2 row_mask:0xf bank_mask:0xf bound_ctrl:0
	s_nop 1
	v_add_f32_dpp v120, v120, v120 row_shr:4 row_mask:0xf bank_mask:0xf bound_ctrl:0
	s_nop 1
	v_add_f32_dpp v120, v120, v120 row_shr:8 row_mask:0xf bank_mask:0xf bound_ctrl:0
	s_nop 1
	v_add_f32_dpp v120, v120, v120 row_bcast:15 row_mask:0xa bank_mask:0xf
	s_nop 1
	v_add_f32_dpp v120, v120, v120 row_bcast:31 row_mask:0xc bank_mask:0xf
	s_nop 1
	v_readlane_b32 s98, v120, 63
	s_nop 1
	s_mov_b32 s2, 0xf800000
	s_waitcnt lgkmcnt(0)
	v_mov_b32_e32 v43, s98
	v_fmac_f32_e32 v36, 0xba800000, v43
	v_fmac_f32_e32 v37, 0xba800000, v43
	v_fmac_f32_e32 v35, 0xba800000, v43
	v_fmac_f32_e32 v34, 0xba800000, v43
	v_mov_b32_e32 v62, v35
	v_mov_b32_e32 v63, v37
	v_mov_b32_e32 v35, v36
	v_pk_mul_f32 v[46:47], v[62:63], v[62:63]
	v_pk_mul_f32 v[36:37], v[34:35], v[34:35]
	v_fmac_f32_e32 v56, 0xba800000, v43
	v_pk_mov_b32 v[66:67], v[36:37], v[46:47] op_sel:[1,0]
	v_mov_b32_e32 v37, v47
	v_mov_b32_e32 v47, v61
	v_mov_b32_e32 v46, v57
	v_mov_b32_e32 v57, v60
	v_pk_add_f32 v[36:37], v[66:67], v[36:37]
	v_fmac_f32_e32 v47, 0xba800000, v43
	v_fmac_f32_e32 v46, 0xba800000, v43
	v_fmac_f32_e32 v57, 0xba800000, v43
	v_pk_add_f32 v[36:37], v[36:37], v[36:37] op_sel_hi:[0,1]
	v_pk_mul_f32 v[60:61], v[46:47], v[46:47]
	v_pk_mul_f32 v[66:67], v[56:57], v[56:57]
	v_fmac_f32_e32 v52, 0xba800000, v43
	v_pk_mov_b32 v[68:69], v[66:67], v[60:61] op_sel:[1,0]
	v_mov_b32_e32 v67, v61
	v_fmac_f32_e32 v54, 0xba800000, v43
	v_fmac_f32_e32 v53, 0xba800000, v43
	v_mul_f32_e32 v36, v52, v52
	v_pk_add_f32 v[60:61], v[68:69], v[66:67]
	v_fmac_f32_e32 v55, 0xba800000, v43
	v_pk_fma_f32 v[66:67], v[52:53], v[52:53], v[36:37] op_sel_hi:[1,1,0]
	v_mul_f32_e32 v36, v54, v54
	v_pk_add_f32 v[60:61], v[60:61], v[60:61] op_sel_hi:[0,1]
	v_pk_fma_f32 v[68:69], v[54:55], v[54:55], v[36:37] op_sel_hi:[1,1,0]
	v_fmac_f32_e32 v49, 0xba800000, v43
	v_fmac_f32_e32 v48, 0xba800000, v43
	v_fmac_f32_e32 v51, 0xba800000, v43
	v_fmac_f32_e32 v50, 0xba800000, v43
	v_mul_f32_e32 v66, v50, v50
	v_mul_f32_e32 v68, v51, v51
	v_mul_f32_e32 v36, v48, v48
	v_mul_f32_e32 v60, v49, v49
	v_pk_add_f32 v[58:59], v[66:67], v[68:69]
	v_pk_add_f32 v[36:37], v[36:37], v[60:61]
	s_nop 0
	v_pk_add_f32 v[36:37], v[58:59], v[36:37]
	s_nop 0
	v_add_f32_e32 v36, v36, v37
	v_mov_b32_e32 v120, v36
	s_nop 1
	v_add_f32_dpp v120, v120, v120 row_shr:1 row_mask:0xf bank_mask:0xf bound_ctrl:0
	s_nop 1
	v_add_f32_dpp v120, v120, v120 row_shr:2 row_mask:0xf bank_mask:0xf bound_ctrl:0
	s_nop 1
	v_add_f32_dpp v120, v120, v120 row_shr:4 row_mask:0xf bank_mask:0xf bound_ctrl:0
	s_nop 1
	v_add_f32_dpp v120, v120, v120 row_shr:8 row_mask:0xf bank_mask:0xf bound_ctrl:0
	s_nop 1
	v_add_f32_dpp v120, v120, v120 row_bcast:15 row_mask:0xa bank_mask:0xf
	s_nop 1
	v_add_f32_dpp v120, v120, v120 row_bcast:31 row_mask:0xc bank_mask:0xf
	s_nop 1
	v_readlane_b32 s98, v120, 63
	s_nop 1
	s_waitcnt lgkmcnt(0)
	v_mov_b32_e32 v36, s98
	v_fmamk_f32 v36, v36, 0x3a800000, v227
	v_mul_f32_e32 v37, 0x4f800000, v36
	v_cmp_gt_f32_e32 vcc, s2, v36
	s_nop 1
	v_cndmask_b32_e32 v36, v36, v37, vcc
	v_sqrt_f32_e32 v37, v36
	s_nop 0
	v_add_u32_e32 v43, -1, v37
	v_fma_f32 v45, -v43, v37, v36
	v_cmp_ge_f32_e64 s[2:3], 0, v45
	v_add_u32_e32 v45, 1, v37
	s_nop 0
	v_cndmask_b32_e64 v43, v37, v43, s[2:3]
	v_fma_f32 v37, -v45, v37, v36
	v_cmp_lt_f32_e64 s[2:3], 0, v37
	s_nop 1
	v_cndmask_b32_e64 v37, v43, v45, s[2:3]
	v_mul_f32_e32 v43, 0x37800000, v37
	v_cndmask_b32_e32 v37, v37, v43, vcc
	v_cmp_class_f32_e32 vcc, v36, v222
	v_ashrrev_i32_e32 v45, 31, v44
	v_lshlrev_b64 v[58:59], 10, v[44:45]
	v_cndmask_b32_e32 v36, v37, v36, vcc
	v_div_scale_f32 v37, s[2:3], v36, v36, 1.0
	v_rcp_f32_e32 v43, v37
	v_or_b32_e32 v58, v58, v38
	v_fma_f32 v44, -v37, v43, 1.0
	v_fmac_f32_e32 v43, v44, v43
	v_div_scale_f32 v44, vcc, 1.0, v36, 1.0
	v_mul_f32_e32 v45, v44, v43
	v_fma_f32 v60, -v37, v45, v44
	v_fmac_f32_e32 v45, v60, v43
	v_fma_f32 v37, -v37, v45, v44
	v_div_fmas_f32 v37, v37, v43, v45
	v_div_fixup_f32 v60, v37, v36, 1.0
	v_pk_mul_f32 v[34:35], v[34:35], v[60:61] op_sel_hi:[1,0]
	v_pk_mul_f32 v[36:37], v[62:63], v[60:61] op_sel_hi:[1,0]
	v_lshl_add_u64 v[44:45], v[58:59], 2, s[4:5]
	v_pk_fma_f32 v[36:37], v[4:5], v[36:37], v[12:13]
	s_and_b64 vcc, exec, s[0:1]
	v_pk_fma_f32 v[34:35], v[2:3], v[34:35], v[10:11]
	s_cbranch_vccnz .LBB0_1644
	global_store_dwordx4 v[44:45], v[34:37], off nt
	v_lshl_add_u64 v[58:59], v[58:59], 1, s[8:9]
	s_cbranch_execnz .LBB0_1624
